# P1 Z stores: cache policy nt -> sc1 nt
# baseline (speedup 1.0000x reference)
; __device__ __forceinline__ unsigned cvt_pk_bf16(float lo, float hi) { unsigned r; asm volatile("v_cvt_pk_bf16_f32 %0, %1, %2" : "=v"(r) : "v"(lo), "v"(hi)); return r; }
; __device__ __forceinline__ float sigm(float x) { return __builtin_amdgcn_rcpf(1.f + __expf(-x)); }
; __device__ __forceinline__ u32x4 pack8(const f32x4 v0, const f32x4 v1) { u32x4 w; w.x = cvt_pk_bf16(v0[0], v0[1]); w.y = cvt_pk_bf16(v0[2], v0[3]); w.z = cvt_pk_bf16(v1[0], v1[1]); w.w = cvt_pk_bf16(v1[2], v1[3]); return w; }
;     __device__ __forceinline__ void operator()(f32x4 (&acc)[2][2][4][2], const Unit& u, int wr, int wc, int fr, int fq) const {
;     ...
;             for (int ai = 0; ai < 2; ++ai)
; #pragma unroll
;                 for (int m = 0; m < 4; ++m) { bf16_t* rowp = base + (size_t)(ai * HALF + m * 16) * LDZ;
; #pragma unroll
;                     for (int bj = 0; bj < 2; ++bj) { f32x4 v0 = acc[ai][bj][m][0], v1 = acc[ai][bj][m][1];
;                         if (kind == 1) {
; #pragma unroll
;                             for (int e = 0; e < 4; ++e) { v0[e] = v0[e] * sigm(v0[e]); v1[e] = v1[e] * sigm(v1[e]); } }
;                         else if (kind == 2) { v0 = v0 * (0.125f * LOG2E); v1 = v1 * (0.125f * LOG2E); }
;                         else if (kind == 3) {
; #pragma unroll
;                             for (int e = 0; e < 4; ++e) { v0[e] = sigm(v0[e] + bv[bj][0][e]); v1[e] = sigm(v1[e] + bv[bj][1][e]); } }
;                         __builtin_nontemporal_store(pack8(v0, v1), (u32x4*)(rowp + bj * HALF)); } }
.Lepi1_k0:
	s_mov_b64 s[6:7], s[50:51]
	v_cvt_pk_bf16_f32 v130, v126, v127
	v_cvt_pk_bf16_f32 v131, v128, v129
	v_cvt_pk_bf16_f32 v132, v122, v123
	v_cvt_pk_bf16_f32 v133, v124, v125
	v_cvt_pk_bf16_f32 v134, v62, v63
	v_cvt_pk_bf16_f32 v135, v64, v65
	v_cvt_pk_bf16_f32 v136, v58, v59
	v_cvt_pk_bf16_f32 v137, v60, v61
	v_mov_b32_e32 v140, v134
	v_mov_b32_e32 v141, v135
	v_mov_b32_e32 v142, v136
	v_mov_b32_e32 v143, v137
	v_mov_b32_dpp v134, v130 row_ror:8 row_mask:0xf bank_mask:0x3
	v_mov_b32_dpp v135, v131 row_ror:8 row_mask:0xf bank_mask:0x3
	v_mov_b32_dpp v136, v132 row_ror:8 row_mask:0xf bank_mask:0x3
	v_mov_b32_dpp v137, v133 row_ror:8 row_mask:0xf bank_mask:0x3
	v_mov_b32_dpp v130, v140 row_ror:8 row_mask:0xf bank_mask:0xc
	v_mov_b32_dpp v131, v141 row_ror:8 row_mask:0xf bank_mask:0xc
	v_mov_b32_dpp v132, v142 row_ror:8 row_mask:0xf bank_mask:0xc
	v_mov_b32_dpp v133, v143 row_ror:8 row_mask:0xf bank_mask:0xc
	global_store_dwordx4 v138, v[130:133], s[6:7] sc1 nt
	global_store_dwordx4 v139, v[134:137], s[6:7] sc1 nt
	s_add_u32 s6, s6, 0x8000
	s_addc_u32 s7, s7, 0
	v_cvt_pk_bf16_f32 v156, v118, v119
	v_cvt_pk_bf16_f32 v157, v120, v121
	v_cvt_pk_bf16_f32 v158, v114, v115
	v_cvt_pk_bf16_f32 v159, v116, v117
	v_cvt_pk_bf16_f32 v160, v54, v55
	v_cvt_pk_bf16_f32 v161, v56, v57
	v_cvt_pk_bf16_f32 v162, v50, v51
	v_cvt_pk_bf16_f32 v163, v52, v53
	v_mov_b32_e32 v188, v160
	v_mov_b32_e32 v189, v161
	v_mov_b32_e32 v190, v162
	v_mov_b32_e32 v191, v163
	v_mov_b32_dpp v160, v156 row_ror:8 row_mask:0xf bank_mask:0x3
	v_mov_b32_dpp v161, v157 row_ror:8 row_mask:0xf bank_mask:0x3
	v_mov_b32_dpp v162, v158 row_ror:8 row_mask:0xf bank_mask:0x3
	v_mov_b32_dpp v163, v159 row_ror:8 row_mask:0xf bank_mask:0x3
	v_mov_b32_dpp v156, v188 row_ror:8 row_mask:0xf bank_mask:0xc
	v_mov_b32_dpp v157, v189 row_ror:8 row_mask:0xf bank_mask:0xc
	v_mov_b32_dpp v158, v190 row_ror:8 row_mask:0xf bank_mask:0xc
	v_mov_b32_dpp v159, v191 row_ror:8 row_mask:0xf bank_mask:0xc
	global_store_dwordx4 v138, v[156:159], s[6:7] sc1 nt
	global_store_dwordx4 v139, v[160:163], s[6:7] sc1 nt
	s_add_u32 s6, s6, 0x8000
	s_addc_u32 s7, s7, 0
	v_cvt_pk_bf16_f32 v130, v110, v111
	v_cvt_pk_bf16_f32 v131, v112, v113
	v_cvt_pk_bf16_f32 v132, v106, v107
	v_cvt_pk_bf16_f32 v133, v108, v109
	v_cvt_pk_bf16_f32 v134, v46, v47
	v_cvt_pk_bf16_f32 v135, v48, v49
	v_cvt_pk_bf16_f32 v136, v42, v43
	v_cvt_pk_bf16_f32 v137, v44, v45
	v_mov_b32_e32 v140, v134
	v_mov_b32_e32 v141, v135
	v_mov_b32_e32 v142, v136
	v_mov_b32_e32 v143, v137
	v_mov_b32_dpp v134, v130 row_ror:8 row_mask:0xf bank_mask:0x3
	v_mov_b32_dpp v135, v131 row_ror:8 row_mask:0xf bank_mask:0x3
	v_mov_b32_dpp v136, v132 row_ror:8 row_mask:0xf bank_mask:0x3
	v_mov_b32_dpp v137, v133 row_ror:8 row_mask:0xf bank_mask:0x3
	v_mov_b32_dpp v130, v140 row_ror:8 row_mask:0xf bank_mask:0xc
	v_mov_b32_dpp v131, v141 row_ror:8 row_mask:0xf bank_mask:0xc
	v_mov_b32_dpp v132, v142 row_ror:8 row_mask:0xf bank_mask:0xc
	v_mov_b32_dpp v133, v143 row_ror:8 row_mask:0xf bank_mask:0xc
	global_store_dwordx4 v138, v[130:133], s[6:7] sc1 nt
	global_store_dwordx4 v139, v[134:137], s[6:7] sc1 nt
	s_add_u32 s6, s6, 0x8000
	s_addc_u32 s7, s7, 0
	v_cvt_pk_bf16_f32 v156, v102, v103
	v_cvt_pk_bf16_f32 v157, v104, v105
	v_cvt_pk_bf16_f32 v158, v98, v99
	v_cvt_pk_bf16_f32 v159, v100, v101
	v_cvt_pk_bf16_f32 v160, v38, v39
	v_cvt_pk_bf16_f32 v161, v40, v41
	v_cvt_pk_bf16_f32 v162, v34, v35
	v_cvt_pk_bf16_f32 v163, v36, v37
	v_mov_b32_e32 v188, v160
	v_mov_b32_e32 v189, v161
	v_mov_b32_e32 v190, v162
	v_mov_b32_e32 v191, v163
	v_mov_b32_dpp v160, v156 row_ror:8 row_mask:0xf bank_mask:0x3
	v_mov_b32_dpp v161, v157 row_ror:8 row_mask:0xf bank_mask:0x3
	v_mov_b32_dpp v162, v158 row_ror:8 row_mask:0xf bank_mask:0x3
	v_mov_b32_dpp v163, v159 row_ror:8 row_mask:0xf bank_mask:0x3
	v_mov_b32_dpp v156, v188 row_ror:8 row_mask:0xf bank_mask:0xc
	v_mov_b32_dpp v157, v189 row_ror:8 row_mask:0xf bank_mask:0xc
	v_mov_b32_dpp v158, v190 row_ror:8 row_mask:0xf bank_mask:0xc
	v_mov_b32_dpp v159, v191 row_ror:8 row_mask:0xf bank_mask:0xc
	global_store_dwordx4 v138, v[156:159], s[6:7] sc1 nt
	global_store_dwordx4 v139, v[160:163], s[6:7] sc1 nt
	s_add_u32 s6, s6, 0x28000
	s_addc_u32 s7, s7, 0
	v_cvt_pk_bf16_f32 v130, v94, v95
	v_cvt_pk_bf16_f32 v131, v96, v97
	v_cvt_pk_bf16_f32 v132, v90, v91
	v_cvt_pk_bf16_f32 v133, v92, v93
	v_cvt_pk_bf16_f32 v134, v30, v31
	v_cvt_pk_bf16_f32 v135, v32, v33
	v_cvt_pk_bf16_f32 v136, v26, v27
	v_cvt_pk_bf16_f32 v137, v28, v29
	v_mov_b32_e32 v140, v134
	v_mov_b32_e32 v141, v135
	v_mov_b32_e32 v142, v136
	v_mov_b32_e32 v143, v137
	v_mov_b32_dpp v134, v130 row_ror:8 row_mask:0xf bank_mask:0x3
	v_mov_b32_dpp v135, v131 row_ror:8 row_mask:0xf bank_mask:0x3
	v_mov_b32_dpp v136, v132 row_ror:8 row_mask:0xf bank_mask:0x3
	v_mov_b32_dpp v137, v133 row_ror:8 row_mask:0xf bank_mask:0x3
	v_mov_b32_dpp v130, v140 row_ror:8 row_mask:0xf bank_mask:0xc
	v_mov_b32_dpp v131, v141 row_ror:8 row_mask:0xf bank_mask:0xc
	v_mov_b32_dpp v132, v142 row_ror:8 row_mask:0xf bank_mask:0xc
	v_mov_b32_dpp v133, v143 row_ror:8 row_mask:0xf bank_mask:0xc
	global_store_dwordx4 v138, v[130:133], s[6:7] sc1 nt
	global_store_dwordx4 v139, v[134:137], s[6:7] sc1 nt
	s_add_u32 s6, s6, 0x8000
	s_addc_u32 s7, s7, 0
	v_cvt_pk_bf16_f32 v156, v86, v87
	v_cvt_pk_bf16_f32 v157, v88, v89
	v_cvt_pk_bf16_f32 v158, v82, v83
	v_cvt_pk_bf16_f32 v159, v84, v85
	v_cvt_pk_bf16_f32 v160, v22, v23
	v_cvt_pk_bf16_f32 v161, v24, v25
	v_cvt_pk_bf16_f32 v162, v18, v19
	v_cvt_pk_bf16_f32 v163, v20, v21
	v_mov_b32_e32 v188, v160
	v_mov_b32_e32 v189, v161
	v_mov_b32_e32 v190, v162
	v_mov_b32_e32 v191, v163
; __device__ __forceinline__ unsigned cvt_pk_bf16(float lo, float hi) { unsigned r; asm volatile("v_cvt_pk_bf16_f32 %0, %1, %2" : "=v"(r) : "v"(lo), "v"(hi)); return r; }
; __device__ __forceinline__ float sigm(float x) { return __builtin_amdgcn_rcpf(1.f + __expf(-x)); }
; __device__ __forceinline__ u32x4 pack8(const f32x4 v0, const f32x4 v1) { u32x4 w; w.x = cvt_pk_bf16(v0[0], v0[1]); w.y = cvt_pk_bf16(v0[2], v0[3]); w.z = cvt_pk_bf16(v1[0], v1[1]); w.w = cvt_pk_bf16(v1[2], v1[3]); return w; }
;     __device__ __forceinline__ void operator()(f32x4 (&acc)[2][2][4][2], const Unit& u, int wr, int wc, int fr, int fq) const {
;     ...
;             for (int ai = 0; ai < 2; ++ai)
; #pragma unroll
;                 for (int m = 0; m < 4; ++m) { bf16_t* rowp = base + (size_t)(ai * HALF + m * 16) * LDZ;
; #pragma unroll
;                     for (int bj = 0; bj < 2; ++bj) { f32x4 v0 = acc[ai][bj][m][0], v1 = acc[ai][bj][m][1];
;                         if (kind == 1) {
; #pragma unroll
;                             for (int e = 0; e < 4; ++e) { v0[e] = v0[e] * sigm(v0[e]); v1[e] = v1[e] * sigm(v1[e]); } }
;                         else if (kind == 2) { v0 = v0 * (0.125f * LOG2E); v1 = v1 * (0.125f * LOG2E); }
;                         else if (kind == 3) {
; #pragma unroll
;                             for (int e = 0; e < 4; ++e) { v0[e] = sigm(v0[e] + bv[bj][0][e]); v1[e] = sigm(v1[e] + bv[bj][1][e]); } }
;                         __builtin_nontemporal_store(pack8(v0, v1), (u32x4*)(rowp + bj * HALF)); } }
	v_mov_b32_dpp v160, v156 row_ror:8 row_mask:0xf bank_mask:0x3
	v_mov_b32_dpp v161, v157 row_ror:8 row_mask:0xf bank_mask:0x3
	v_mov_b32_dpp v162, v158 row_ror:8 row_mask:0xf bank_mask:0x3
	v_mov_b32_dpp v163, v159 row_ror:8 row_mask:0xf bank_mask:0x3
	v_mov_b32_dpp v156, v188 row_ror:8 row_mask:0xf bank_mask:0xc
	v_mov_b32_dpp v157, v189 row_ror:8 row_mask:0xf bank_mask:0xc
	v_mov_b32_dpp v158, v190 row_ror:8 row_mask:0xf bank_mask:0xc
	v_mov_b32_dpp v159, v191 row_ror:8 row_mask:0xf bank_mask:0xc
	global_store_dwordx4 v138, v[156:159], s[6:7] sc1 nt
	global_store_dwordx4 v139, v[160:163], s[6:7] sc1 nt
	s_add_u32 s6, s6, 0x8000
	s_addc_u32 s7, s7, 0
	v_cvt_pk_bf16_f32 v130, v78, v79
	v_cvt_pk_bf16_f32 v131, v80, v81
	v_cvt_pk_bf16_f32 v132, v74, v75
	v_cvt_pk_bf16_f32 v133, v76, v77
	v_cvt_pk_bf16_f32 v134, v14, v15
	v_cvt_pk_bf16_f32 v135, v16, v17
	v_cvt_pk_bf16_f32 v136, v10, v11
	v_cvt_pk_bf16_f32 v137, v12, v13
	v_mov_b32_e32 v140, v134
	v_mov_b32_e32 v141, v135
	v_mov_b32_e32 v142, v136
	v_mov_b32_e32 v143, v137
	v_mov_b32_dpp v134, v130 row_ror:8 row_mask:0xf bank_mask:0x3
	v_mov_b32_dpp v135, v131 row_ror:8 row_mask:0xf bank_mask:0x3
	v_mov_b32_dpp v136, v132 row_ror:8 row_mask:0xf bank_mask:0x3
	v_mov_b32_dpp v137, v133 row_ror:8 row_mask:0xf bank_mask:0x3
	v_mov_b32_dpp v130, v140 row_ror:8 row_mask:0xf bank_mask:0xc
	v_mov_b32_dpp v131, v141 row_ror:8 row_mask:0xf bank_mask:0xc
	v_mov_b32_dpp v132, v142 row_ror:8 row_mask:0xf bank_mask:0xc
	v_mov_b32_dpp v133, v143 row_ror:8 row_mask:0xf bank_mask:0xc
	global_store_dwordx4 v138, v[130:133], s[6:7] sc1 nt
	global_store_dwordx4 v139, v[134:137], s[6:7] sc1 nt
	s_add_u32 s6, s6, 0x8000
	s_addc_u32 s7, s7, 0
	v_cvt_pk_bf16_f32 v156, v70, v71
	v_cvt_pk_bf16_f32 v157, v72, v73
	v_cvt_pk_bf16_f32 v158, v66, v67
	v_cvt_pk_bf16_f32 v159, v68, v69
	v_cvt_pk_bf16_f32 v160, v6, v7
	v_cvt_pk_bf16_f32 v161, v8, v9
	v_cvt_pk_bf16_f32 v162, v2, v3
	v_cvt_pk_bf16_f32 v163, v4, v5
	v_mov_b32_e32 v188, v160
	v_mov_b32_e32 v189, v161
	v_mov_b32_e32 v190, v162
	v_mov_b32_e32 v191, v163
	v_mov_b32_dpp v160, v156 row_ror:8 row_mask:0xf bank_mask:0x3
	v_mov_b32_dpp v161, v157 row_ror:8 row_mask:0xf bank_mask:0x3
	v_mov_b32_dpp v162, v158 row_ror:8 row_mask:0xf bank_mask:0x3
	v_mov_b32_dpp v163, v159 row_ror:8 row_mask:0xf bank_mask:0x3
	v_mov_b32_dpp v156, v188 row_ror:8 row_mask:0xf bank_mask:0xc
	v_mov_b32_dpp v157, v189 row_ror:8 row_mask:0xf bank_mask:0xc
	v_mov_b32_dpp v158, v190 row_ror:8 row_mask:0xf bank_mask:0xc
	v_mov_b32_dpp v159, v191 row_ror:8 row_mask:0xf bank_mask:0xc
	global_store_dwordx4 v138, v[156:159], s[6:7] sc1 nt
	global_store_dwordx4 v139, v[160:163], s[6:7] sc1 nt
	s_branch .Lepi1_done
.Lepi1_k1:
	s_mov_b64 s[6:7], s[50:51]
	v_pk_mul_f32 v[172:173], v[126:127], s[24:25] op_sel_hi:[1,0]
	v_pk_mul_f32 v[174:175], v[128:129], s[24:25] op_sel_hi:[1,0]
	v_pk_mul_f32 v[176:177], v[122:123], s[24:25] op_sel_hi:[1,0]
	v_pk_mul_f32 v[178:179], v[124:125], s[24:25] op_sel_hi:[1,0]
	v_exp_f32_e32 v172, v172
	v_exp_f32_e32 v173, v173
	v_exp_f32_e32 v174, v174
	v_exp_f32_e32 v175, v175
	v_exp_f32_e32 v176, v176
	v_exp_f32_e32 v177, v177
	v_exp_f32_e32 v178, v178
	v_exp_f32_e32 v179, v179
	v_pk_add_f32 v[172:173], v[172:173], 1.0 op_sel_hi:[1,0]
	v_pk_add_f32 v[174:175], v[174:175], 1.0 op_sel_hi:[1,0]
	v_pk_add_f32 v[176:177], v[176:177], 1.0 op_sel_hi:[1,0]
	v_pk_add_f32 v[178:179], v[178:179], 1.0 op_sel_hi:[1,0]
	v_rcp_f32_e32 v172, v172
	v_rcp_f32_e32 v173, v173
	v_rcp_f32_e32 v174, v174
	v_rcp_f32_e32 v175, v175
	v_rcp_f32_e32 v176, v176
	v_rcp_f32_e32 v177, v177
	v_rcp_f32_e32 v178, v178
	v_rcp_f32_e32 v179, v179
	v_pk_mul_f32 v[172:173], v[126:127], v[172:173]
	v_pk_mul_f32 v[174:175], v[128:129], v[174:175]
	v_pk_mul_f32 v[176:177], v[122:123], v[176:177]
	v_pk_mul_f32 v[178:179], v[124:125], v[178:179]
	v_pk_mul_f32 v[180:181], v[62:63], s[24:25] op_sel_hi:[1,0]
	v_pk_mul_f32 v[182:183], v[64:65], s[24:25] op_sel_hi:[1,0]
	v_pk_mul_f32 v[184:185], v[58:59], s[24:25] op_sel_hi:[1,0]
	v_pk_mul_f32 v[186:187], v[60:61], s[24:25] op_sel_hi:[1,0]
	v_exp_f32_e32 v180, v180
	v_exp_f32_e32 v181, v181
	v_exp_f32_e32 v182, v182
	v_exp_f32_e32 v183, v183
	v_exp_f32_e32 v184, v184
	v_exp_f32_e32 v185, v185
	v_exp_f32_e32 v186, v186
	v_exp_f32_e32 v187, v187
	v_pk_add_f32 v[180:181], v[180:181], 1.0 op_sel_hi:[1,0]
	v_pk_add_f32 v[182:183], v[182:183], 1.0 op_sel_hi:[1,0]
	v_pk_add_f32 v[184:185], v[184:185], 1.0 op_sel_hi:[1,0]
	v_pk_add_f32 v[186:187], v[186:187], 1.0 op_sel_hi:[1,0]
	v_rcp_f32_e32 v180, v180
	v_rcp_f32_e32 v181, v181
	v_rcp_f32_e32 v182, v182
	v_rcp_f32_e32 v183, v183
	v_rcp_f32_e32 v184, v184
	v_rcp_f32_e32 v185, v185
	v_rcp_f32_e32 v186, v186
	v_rcp_f32_e32 v187, v187
	v_pk_mul_f32 v[180:181], v[62:63], v[180:181]
	v_pk_mul_f32 v[182:183], v[64:65], v[182:183]
	v_pk_mul_f32 v[184:185], v[58:59], v[184:185]
	v_pk_mul_f32 v[186:187], v[60:61], v[186:187]
	v_cvt_pk_bf16_f32 v130, v172, v173
	v_cvt_pk_bf16_f32 v131, v174, v175
	v_cvt_pk_bf16_f32 v132, v176, v177
	v_cvt_pk_bf16_f32 v133, v178, v179
	v_cvt_pk_bf16_f32 v134, v180, v181
	v_cvt_pk_bf16_f32 v135, v182, v183
	v_cvt_pk_bf16_f32 v136, v184, v185
	v_cvt_pk_bf16_f32 v137, v186, v187
	v_mov_b32_e32 v140, v134
	v_mov_b32_e32 v141, v135
	v_mov_b32_e32 v142, v136
	v_mov_b32_e32 v143, v137
	v_mov_b32_dpp v134, v130 row_ror:8 row_mask:0xf bank_mask:0x3
	v_mov_b32_dpp v135, v131 row_ror:8 row_mask:0xf bank_mask:0x3
	v_mov_b32_dpp v136, v132 row_ror:8 row_mask:0xf bank_mask:0x3
	v_mov_b32_dpp v137, v133 row_ror:8 row_mask:0xf bank_mask:0x3
	v_mov_b32_dpp v130, v140 row_ror:8 row_mask:0xf bank_mask:0xc
; __device__ __forceinline__ unsigned cvt_pk_bf16(float lo, float hi) { unsigned r; asm volatile("v_cvt_pk_bf16_f32 %0, %1, %2" : "=v"(r) : "v"(lo), "v"(hi)); return r; }
; __device__ __forceinline__ float sigm(float x) { return __builtin_amdgcn_rcpf(1.f + __expf(-x)); }
; __device__ __forceinline__ u32x4 pack8(const f32x4 v0, const f32x4 v1) { u32x4 w; w.x = cvt_pk_bf16(v0[0], v0[1]); w.y = cvt_pk_bf16(v0[2], v0[3]); w.z = cvt_pk_bf16(v1[0], v1[1]); w.w = cvt_pk_bf16(v1[2], v1[3]); return w; }
;     __device__ __forceinline__ void operator()(f32x4 (&acc)[2][2][4][2], const Unit& u, int wr, int wc, int fr, int fq) const {
;     ...
;             for (int ai = 0; ai < 2; ++ai)
; #pragma unroll
;                 for (int m = 0; m < 4; ++m) { bf16_t* rowp = base + (size_t)(ai * HALF + m * 16) * LDZ;
; #pragma unroll
;                     for (int bj = 0; bj < 2; ++bj) { f32x4 v0 = acc[ai][bj][m][0], v1 = acc[ai][bj][m][1];
;                         if (kind == 1) {
; #pragma unroll
;                             for (int e = 0; e < 4; ++e) { v0[e] = v0[e] * sigm(v0[e]); v1[e] = v1[e] * sigm(v1[e]); } }
;                         else if (kind == 2) { v0 = v0 * (0.125f * LOG2E); v1 = v1 * (0.125f * LOG2E); }
;                         else if (kind == 3) {
; #pragma unroll
;                             for (int e = 0; e < 4; ++e) { v0[e] = sigm(v0[e] + bv[bj][0][e]); v1[e] = sigm(v1[e] + bv[bj][1][e]); } }
;                         __builtin_nontemporal_store(pack8(v0, v1), (u32x4*)(rowp + bj * HALF)); } }
	v_mov_b32_dpp v131, v141 row_ror:8 row_mask:0xf bank_mask:0xc
	v_mov_b32_dpp v132, v142 row_ror:8 row_mask:0xf bank_mask:0xc
	v_mov_b32_dpp v133, v143 row_ror:8 row_mask:0xf bank_mask:0xc
	global_store_dwordx4 v138, v[130:133], s[6:7] sc1 nt
	global_store_dwordx4 v139, v[134:137], s[6:7] sc1 nt
	s_add_u32 s6, s6, 0x8000
	s_addc_u32 s7, s7, 0
	v_pk_mul_f32 v[206:207], v[118:119], s[24:25] op_sel_hi:[1,0]
	v_pk_mul_f32 v[208:209], v[120:121], s[24:25] op_sel_hi:[1,0]
	v_pk_mul_f32 v[210:211], v[114:115], s[24:25] op_sel_hi:[1,0]
	v_pk_mul_f32 v[212:213], v[116:117], s[24:25] op_sel_hi:[1,0]
	v_exp_f32_e32 v206, v206
	v_exp_f32_e32 v207, v207
	v_exp_f32_e32 v208, v208
	v_exp_f32_e32 v209, v209
	v_exp_f32_e32 v210, v210
	v_exp_f32_e32 v211, v211
	v_exp_f32_e32 v212, v212
	v_exp_f32_e32 v213, v213
	v_pk_add_f32 v[206:207], v[206:207], 1.0 op_sel_hi:[1,0]
	v_pk_add_f32 v[208:209], v[208:209], 1.0 op_sel_hi:[1,0]
	v_pk_add_f32 v[210:211], v[210:211], 1.0 op_sel_hi:[1,0]
	v_pk_add_f32 v[212:213], v[212:213], 1.0 op_sel_hi:[1,0]
	v_rcp_f32_e32 v206, v206
	v_rcp_f32_e32 v207, v207
	v_rcp_f32_e32 v208, v208
	v_rcp_f32_e32 v209, v209
	v_rcp_f32_e32 v210, v210
	v_rcp_f32_e32 v211, v211
	v_rcp_f32_e32 v212, v212
	v_rcp_f32_e32 v213, v213
	v_pk_mul_f32 v[206:207], v[118:119], v[206:207]
	v_pk_mul_f32 v[208:209], v[120:121], v[208:209]
	v_pk_mul_f32 v[210:211], v[114:115], v[210:211]
	v_pk_mul_f32 v[212:213], v[116:117], v[212:213]
	v_pk_mul_f32 v[214:215], v[54:55], s[24:25] op_sel_hi:[1,0]
	v_pk_mul_f32 v[216:217], v[56:57], s[24:25] op_sel_hi:[1,0]
	v_pk_mul_f32 v[218:219], v[50:51], s[24:25] op_sel_hi:[1,0]
	v_pk_mul_f32 v[220:221], v[52:53], s[24:25] op_sel_hi:[1,0]
	v_exp_f32_e32 v214, v214
	v_exp_f32_e32 v215, v215
	v_exp_f32_e32 v216, v216
	v_exp_f32_e32 v217, v217
	v_exp_f32_e32 v218, v218
	v_exp_f32_e32 v219, v219
	v_exp_f32_e32 v220, v220
	v_exp_f32_e32 v221, v221
	v_pk_add_f32 v[214:215], v[214:215], 1.0 op_sel_hi:[1,0]
	v_pk_add_f32 v[216:217], v[216:217], 1.0 op_sel_hi:[1,0]
	v_pk_add_f32 v[218:219], v[218:219], 1.0 op_sel_hi:[1,0]
	v_pk_add_f32 v[220:221], v[220:221], 1.0 op_sel_hi:[1,0]
	v_rcp_f32_e32 v214, v214
	v_rcp_f32_e32 v215, v215
	v_rcp_f32_e32 v216, v216
	v_rcp_f32_e32 v217, v217
	v_rcp_f32_e32 v218, v218
	v_rcp_f32_e32 v219, v219
	v_rcp_f32_e32 v220, v220
	v_rcp_f32_e32 v221, v221
	v_pk_mul_f32 v[214:215], v[54:55], v[214:215]
	v_pk_mul_f32 v[216:217], v[56:57], v[216:217]
	v_pk_mul_f32 v[218:219], v[50:51], v[218:219]
	v_pk_mul_f32 v[220:221], v[52:53], v[220:221]
	v_cvt_pk_bf16_f32 v156, v206, v207
	v_cvt_pk_bf16_f32 v157, v208, v209
	v_cvt_pk_bf16_f32 v158, v210, v211
	v_cvt_pk_bf16_f32 v159, v212, v213
	v_cvt_pk_bf16_f32 v160, v214, v215
	v_cvt_pk_bf16_f32 v161, v216, v217
	v_cvt_pk_bf16_f32 v162, v218, v219
	v_cvt_pk_bf16_f32 v163, v220, v221
	v_mov_b32_e32 v188, v160
	v_mov_b32_e32 v189, v161
	v_mov_b32_e32 v190, v162
	v_mov_b32_e32 v191, v163
	v_mov_b32_dpp v160, v156 row_ror:8 row_mask:0xf bank_mask:0x3
	v_mov_b32_dpp v161, v157 row_ror:8 row_mask:0xf bank_mask:0x3
	v_mov_b32_dpp v162, v158 row_ror:8 row_mask:0xf bank_mask:0x3
	v_mov_b32_dpp v163, v159 row_ror:8 row_mask:0xf bank_mask:0x3
	v_mov_b32_dpp v156, v188 row_ror:8 row_mask:0xf bank_mask:0xc
	v_mov_b32_dpp v157, v189 row_ror:8 row_mask:0xf bank_mask:0xc
	v_mov_b32_dpp v158, v190 row_ror:8 row_mask:0xf bank_mask:0xc
	v_mov_b32_dpp v159, v191 row_ror:8 row_mask:0xf bank_mask:0xc
	global_store_dwordx4 v138, v[156:159], s[6:7] sc1 nt
	global_store_dwordx4 v139, v[160:163], s[6:7] sc1 nt
	s_add_u32 s6, s6, 0x8000
	s_addc_u32 s7, s7, 0
	v_pk_mul_f32 v[172:173], v[110:111], s[24:25] op_sel_hi:[1,0]
	v_pk_mul_f32 v[174:175], v[112:113], s[24:25] op_sel_hi:[1,0]
	v_pk_mul_f32 v[176:177], v[106:107], s[24:25] op_sel_hi:[1,0]
	v_pk_mul_f32 v[178:179], v[108:109], s[24:25] op_sel_hi:[1,0]
	v_exp_f32_e32 v172, v172
	v_exp_f32_e32 v173, v173
	v_exp_f32_e32 v174, v174
	v_exp_f32_e32 v175, v175
	v_exp_f32_e32 v176, v176
	v_exp_f32_e32 v177, v177
	v_exp_f32_e32 v178, v178
	v_exp_f32_e32 v179, v179
	v_pk_add_f32 v[172:173], v[172:173], 1.0 op_sel_hi:[1,0]
	v_pk_add_f32 v[174:175], v[174:175], 1.0 op_sel_hi:[1,0]
	v_pk_add_f32 v[176:177], v[176:177], 1.0 op_sel_hi:[1,0]
	v_pk_add_f32 v[178:179], v[178:179], 1.0 op_sel_hi:[1,0]
	v_rcp_f32_e32 v172, v172
	v_rcp_f32_e32 v173, v173
	v_rcp_f32_e32 v174, v174
	v_rcp_f32_e32 v175, v175
	v_rcp_f32_e32 v176, v176
	v_rcp_f32_e32 v177, v177
	v_rcp_f32_e32 v178, v178
	v_rcp_f32_e32 v179, v179
	v_pk_mul_f32 v[172:173], v[110:111], v[172:173]
	v_pk_mul_f32 v[174:175], v[112:113], v[174:175]
	v_pk_mul_f32 v[176:177], v[106:107], v[176:177]
	v_pk_mul_f32 v[178:179], v[108:109], v[178:179]
	v_pk_mul_f32 v[180:181], v[46:47], s[24:25] op_sel_hi:[1,0]
	v_pk_mul_f32 v[182:183], v[48:49], s[24:25] op_sel_hi:[1,0]
	v_pk_mul_f32 v[184:185], v[42:43], s[24:25] op_sel_hi:[1,0]
	v_pk_mul_f32 v[186:187], v[44:45], s[24:25] op_sel_hi:[1,0]
	v_exp_f32_e32 v180, v180
	v_exp_f32_e32 v181, v181
	v_exp_f32_e32 v182, v182
	v_exp_f32_e32 v183, v183
	v_exp_f32_e32 v184, v184
	v_exp_f32_e32 v185, v185
	v_exp_f32_e32 v186, v186
	v_exp_f32_e32 v187, v187
	v_pk_add_f32 v[180:181], v[180:181], 1.0 op_sel_hi:[1,0]
	v_pk_add_f32 v[182:183], v[182:183], 1.0 op_sel_hi:[1,0]
	v_pk_add_f32 v[184:185], v[184:185], 1.0 op_sel_hi:[1,0]
	v_pk_add_f32 v[186:187], v[186:187], 1.0 op_sel_hi:[1,0]
	v_rcp_f32_e32 v180, v180
	v_rcp_f32_e32 v181, v181
	v_rcp_f32_e32 v182, v182
	v_rcp_f32_e32 v183, v183
	v_rcp_f32_e32 v184, v184
	v_rcp_f32_e32 v185, v185
	v_rcp_f32_e32 v186, v186
	v_rcp_f32_e32 v187, v187
	v_pk_mul_f32 v[180:181], v[46:47], v[180:181]
	v_pk_mul_f32 v[182:183], v[48:49], v[182:183]
; __device__ __forceinline__ unsigned cvt_pk_bf16(float lo, float hi) { unsigned r; asm volatile("v_cvt_pk_bf16_f32 %0, %1, %2" : "=v"(r) : "v"(lo), "v"(hi)); return r; }
; __device__ __forceinline__ float sigm(float x) { return __builtin_amdgcn_rcpf(1.f + __expf(-x)); }
; __device__ __forceinline__ u32x4 pack8(const f32x4 v0, const f32x4 v1) { u32x4 w; w.x = cvt_pk_bf16(v0[0], v0[1]); w.y = cvt_pk_bf16(v0[2], v0[3]); w.z = cvt_pk_bf16(v1[0], v1[1]); w.w = cvt_pk_bf16(v1[2], v1[3]); return w; }
;     __device__ __forceinline__ void operator()(f32x4 (&acc)[2][2][4][2], const Unit& u, int wr, int wc, int fr, int fq) const {
;     ...
;             for (int ai = 0; ai < 2; ++ai)
; #pragma unroll
;                 for (int m = 0; m < 4; ++m) { bf16_t* rowp = base + (size_t)(ai * HALF + m * 16) * LDZ;
; #pragma unroll
;                     for (int bj = 0; bj < 2; ++bj) { f32x4 v0 = acc[ai][bj][m][0], v1 = acc[ai][bj][m][1];
;                         if (kind == 1) {
; #pragma unroll
;                             for (int e = 0; e < 4; ++e) { v0[e] = v0[e] * sigm(v0[e]); v1[e] = v1[e] * sigm(v1[e]); } }
;                         else if (kind == 2) { v0 = v0 * (0.125f * LOG2E); v1 = v1 * (0.125f * LOG2E); }
;                         else if (kind == 3) {
; #pragma unroll
;                             for (int e = 0; e < 4; ++e) { v0[e] = sigm(v0[e] + bv[bj][0][e]); v1[e] = sigm(v1[e] + bv[bj][1][e]); } }
;                         __builtin_nontemporal_store(pack8(v0, v1), (u32x4*)(rowp + bj * HALF)); } }
	v_pk_mul_f32 v[184:185], v[42:43], v[184:185]
	v_pk_mul_f32 v[186:187], v[44:45], v[186:187]
	v_cvt_pk_bf16_f32 v130, v172, v173
	v_cvt_pk_bf16_f32 v131, v174, v175
	v_cvt_pk_bf16_f32 v132, v176, v177
	v_cvt_pk_bf16_f32 v133, v178, v179
	v_cvt_pk_bf16_f32 v134, v180, v181
	v_cvt_pk_bf16_f32 v135, v182, v183
	v_cvt_pk_bf16_f32 v136, v184, v185
	v_cvt_pk_bf16_f32 v137, v186, v187
	v_mov_b32_e32 v140, v134
	v_mov_b32_e32 v141, v135
	v_mov_b32_e32 v142, v136
	v_mov_b32_e32 v143, v137
	v_mov_b32_dpp v134, v130 row_ror:8 row_mask:0xf bank_mask:0x3
	v_mov_b32_dpp v135, v131 row_ror:8 row_mask:0xf bank_mask:0x3
	v_mov_b32_dpp v136, v132 row_ror:8 row_mask:0xf bank_mask:0x3
	v_mov_b32_dpp v137, v133 row_ror:8 row_mask:0xf bank_mask:0x3
	v_mov_b32_dpp v130, v140 row_ror:8 row_mask:0xf bank_mask:0xc
	v_mov_b32_dpp v131, v141 row_ror:8 row_mask:0xf bank_mask:0xc
	v_mov_b32_dpp v132, v142 row_ror:8 row_mask:0xf bank_mask:0xc
	v_mov_b32_dpp v133, v143 row_ror:8 row_mask:0xf bank_mask:0xc
	global_store_dwordx4 v138, v[130:133], s[6:7] sc1 nt
	global_store_dwordx4 v139, v[134:137], s[6:7] sc1 nt
	s_add_u32 s6, s6, 0x8000
	s_addc_u32 s7, s7, 0
	v_pk_mul_f32 v[206:207], v[102:103], s[24:25] op_sel_hi:[1,0]
	v_pk_mul_f32 v[208:209], v[104:105], s[24:25] op_sel_hi:[1,0]
	v_pk_mul_f32 v[210:211], v[98:99], s[24:25] op_sel_hi:[1,0]
	v_pk_mul_f32 v[212:213], v[100:101], s[24:25] op_sel_hi:[1,0]
	v_exp_f32_e32 v206, v206
	v_exp_f32_e32 v207, v207
	v_exp_f32_e32 v208, v208
	v_exp_f32_e32 v209, v209
	v_exp_f32_e32 v210, v210
	v_exp_f32_e32 v211, v211
	v_exp_f32_e32 v212, v212
	v_exp_f32_e32 v213, v213
	v_pk_add_f32 v[206:207], v[206:207], 1.0 op_sel_hi:[1,0]
	v_pk_add_f32 v[208:209], v[208:209], 1.0 op_sel_hi:[1,0]
	v_pk_add_f32 v[210:211], v[210:211], 1.0 op_sel_hi:[1,0]
	v_pk_add_f32 v[212:213], v[212:213], 1.0 op_sel_hi:[1,0]
	v_rcp_f32_e32 v206, v206
	v_rcp_f32_e32 v207, v207
	v_rcp_f32_e32 v208, v208
	v_rcp_f32_e32 v209, v209
	v_rcp_f32_e32 v210, v210
	v_rcp_f32_e32 v211, v211
	v_rcp_f32_e32 v212, v212
	v_rcp_f32_e32 v213, v213
	v_pk_mul_f32 v[206:207], v[102:103], v[206:207]
	v_pk_mul_f32 v[208:209], v[104:105], v[208:209]
	v_pk_mul_f32 v[210:211], v[98:99], v[210:211]
	v_pk_mul_f32 v[212:213], v[100:101], v[212:213]
	v_pk_mul_f32 v[214:215], v[38:39], s[24:25] op_sel_hi:[1,0]
	v_pk_mul_f32 v[216:217], v[40:41], s[24:25] op_sel_hi:[1,0]
	v_pk_mul_f32 v[218:219], v[34:35], s[24:25] op_sel_hi:[1,0]
	v_pk_mul_f32 v[220:221], v[36:37], s[24:25] op_sel_hi:[1,0]
	v_exp_f32_e32 v214, v214
	v_exp_f32_e32 v215, v215
	v_exp_f32_e32 v216, v216
	v_exp_f32_e32 v217, v217
	v_exp_f32_e32 v218, v218
	v_exp_f32_e32 v219, v219
	v_exp_f32_e32 v220, v220
	v_exp_f32_e32 v221, v221
	v_pk_add_f32 v[214:215], v[214:215], 1.0 op_sel_hi:[1,0]
	v_pk_add_f32 v[216:217], v[216:217], 1.0 op_sel_hi:[1,0]
	v_pk_add_f32 v[218:219], v[218:219], 1.0 op_sel_hi:[1,0]
	v_pk_add_f32 v[220:221], v[220:221], 1.0 op_sel_hi:[1,0]
	v_rcp_f32_e32 v214, v214
	v_rcp_f32_e32 v215, v215
	v_rcp_f32_e32 v216, v216
	v_rcp_f32_e32 v217, v217
	v_rcp_f32_e32 v218, v218
	v_rcp_f32_e32 v219, v219
	v_rcp_f32_e32 v220, v220
	v_rcp_f32_e32 v221, v221
	v_pk_mul_f32 v[214:215], v[38:39], v[214:215]
	v_pk_mul_f32 v[216:217], v[40:41], v[216:217]
	v_pk_mul_f32 v[218:219], v[34:35], v[218:219]
	v_pk_mul_f32 v[220:221], v[36:37], v[220:221]
	v_cvt_pk_bf16_f32 v156, v206, v207
	v_cvt_pk_bf16_f32 v157, v208, v209
	v_cvt_pk_bf16_f32 v158, v210, v211
	v_cvt_pk_bf16_f32 v159, v212, v213
	v_cvt_pk_bf16_f32 v160, v214, v215
	v_cvt_pk_bf16_f32 v161, v216, v217
	v_cvt_pk_bf16_f32 v162, v218, v219
	v_cvt_pk_bf16_f32 v163, v220, v221
	v_mov_b32_e32 v188, v160
	v_mov_b32_e32 v189, v161
	v_mov_b32_e32 v190, v162
	v_mov_b32_e32 v191, v163
	v_mov_b32_dpp v160, v156 row_ror:8 row_mask:0xf bank_mask:0x3
	v_mov_b32_dpp v161, v157 row_ror:8 row_mask:0xf bank_mask:0x3
	v_mov_b32_dpp v162, v158 row_ror:8 row_mask:0xf bank_mask:0x3
	v_mov_b32_dpp v163, v159 row_ror:8 row_mask:0xf bank_mask:0x3
	v_mov_b32_dpp v156, v188 row_ror:8 row_mask:0xf bank_mask:0xc
	v_mov_b32_dpp v157, v189 row_ror:8 row_mask:0xf bank_mask:0xc
	v_mov_b32_dpp v158, v190 row_ror:8 row_mask:0xf bank_mask:0xc
	v_mov_b32_dpp v159, v191 row_ror:8 row_mask:0xf bank_mask:0xc
	global_store_dwordx4 v138, v[156:159], s[6:7] sc1 nt
	global_store_dwordx4 v139, v[160:163], s[6:7] sc1 nt
	s_add_u32 s6, s6, 0x28000
	s_addc_u32 s7, s7, 0
	v_pk_mul_f32 v[172:173], v[94:95], s[24:25] op_sel_hi:[1,0]
	v_pk_mul_f32 v[174:175], v[96:97], s[24:25] op_sel_hi:[1,0]
	v_pk_mul_f32 v[176:177], v[90:91], s[24:25] op_sel_hi:[1,0]
	v_pk_mul_f32 v[178:179], v[92:93], s[24:25] op_sel_hi:[1,0]
	v_exp_f32_e32 v172, v172
	v_exp_f32_e32 v173, v173
	v_exp_f32_e32 v174, v174
	v_exp_f32_e32 v175, v175
	v_exp_f32_e32 v176, v176
	v_exp_f32_e32 v177, v177
	v_exp_f32_e32 v178, v178
	v_exp_f32_e32 v179, v179
	v_pk_add_f32 v[172:173], v[172:173], 1.0 op_sel_hi:[1,0]
	v_pk_add_f32 v[174:175], v[174:175], 1.0 op_sel_hi:[1,0]
	v_pk_add_f32 v[176:177], v[176:177], 1.0 op_sel_hi:[1,0]
	v_pk_add_f32 v[178:179], v[178:179], 1.0 op_sel_hi:[1,0]
	v_rcp_f32_e32 v172, v172
	v_rcp_f32_e32 v173, v173
	v_rcp_f32_e32 v174, v174
	v_rcp_f32_e32 v175, v175
	v_rcp_f32_e32 v176, v176
	v_rcp_f32_e32 v177, v177
	v_rcp_f32_e32 v178, v178
	v_rcp_f32_e32 v179, v179
	v_pk_mul_f32 v[172:173], v[94:95], v[172:173]
	v_pk_mul_f32 v[174:175], v[96:97], v[174:175]
	v_pk_mul_f32 v[176:177], v[90:91], v[176:177]
	v_pk_mul_f32 v[178:179], v[92:93], v[178:179]
	v_pk_mul_f32 v[180:181], v[30:31], s[24:25] op_sel_hi:[1,0]
	v_pk_mul_f32 v[182:183], v[32:33], s[24:25] op_sel_hi:[1,0]
	v_pk_mul_f32 v[184:185], v[26:27], s[24:25] op_sel_hi:[1,0]
; __device__ __forceinline__ unsigned cvt_pk_bf16(float lo, float hi) { unsigned r; asm volatile("v_cvt_pk_bf16_f32 %0, %1, %2" : "=v"(r) : "v"(lo), "v"(hi)); return r; }
; __device__ __forceinline__ float sigm(float x) { return __builtin_amdgcn_rcpf(1.f + __expf(-x)); }
; __device__ __forceinline__ u32x4 pack8(const f32x4 v0, const f32x4 v1) { u32x4 w; w.x = cvt_pk_bf16(v0[0], v0[1]); w.y = cvt_pk_bf16(v0[2], v0[3]); w.z = cvt_pk_bf16(v1[0], v1[1]); w.w = cvt_pk_bf16(v1[2], v1[3]); return w; }
;     __device__ __forceinline__ void operator()(f32x4 (&acc)[2][2][4][2], const Unit& u, int wr, int wc, int fr, int fq) const {
;     ...
;             for (int ai = 0; ai < 2; ++ai)
; #pragma unroll
;                 for (int m = 0; m < 4; ++m) { bf16_t* rowp = base + (size_t)(ai * HALF + m * 16) * LDZ;
; #pragma unroll
;                     for (int bj = 0; bj < 2; ++bj) { f32x4 v0 = acc[ai][bj][m][0], v1 = acc[ai][bj][m][1];
;                         if (kind == 1) {
; #pragma unroll
;                             for (int e = 0; e < 4; ++e) { v0[e] = v0[e] * sigm(v0[e]); v1[e] = v1[e] * sigm(v1[e]); } }
;                         else if (kind == 2) { v0 = v0 * (0.125f * LOG2E); v1 = v1 * (0.125f * LOG2E); }
;                         else if (kind == 3) {
; #pragma unroll
;                             for (int e = 0; e < 4; ++e) { v0[e] = sigm(v0[e] + bv[bj][0][e]); v1[e] = sigm(v1[e] + bv[bj][1][e]); } }
;                         __builtin_nontemporal_store(pack8(v0, v1), (u32x4*)(rowp + bj * HALF)); } }
	v_pk_mul_f32 v[186:187], v[28:29], s[24:25] op_sel_hi:[1,0]
	v_exp_f32_e32 v180, v180
	v_exp_f32_e32 v181, v181
	v_exp_f32_e32 v182, v182
	v_exp_f32_e32 v183, v183
	v_exp_f32_e32 v184, v184
	v_exp_f32_e32 v185, v185
	v_exp_f32_e32 v186, v186
	v_exp_f32_e32 v187, v187
	v_pk_add_f32 v[180:181], v[180:181], 1.0 op_sel_hi:[1,0]
	v_pk_add_f32 v[182:183], v[182:183], 1.0 op_sel_hi:[1,0]
	v_pk_add_f32 v[184:185], v[184:185], 1.0 op_sel_hi:[1,0]
	v_pk_add_f32 v[186:187], v[186:187], 1.0 op_sel_hi:[1,0]
	v_rcp_f32_e32 v180, v180
	v_rcp_f32_e32 v181, v181
	v_rcp_f32_e32 v182, v182
	v_rcp_f32_e32 v183, v183
	v_rcp_f32_e32 v184, v184
	v_rcp_f32_e32 v185, v185
	v_rcp_f32_e32 v186, v186
	v_rcp_f32_e32 v187, v187
	v_pk_mul_f32 v[180:181], v[30:31], v[180:181]
	v_pk_mul_f32 v[182:183], v[32:33], v[182:183]
	v_pk_mul_f32 v[184:185], v[26:27], v[184:185]
	v_pk_mul_f32 v[186:187], v[28:29], v[186:187]
	v_cvt_pk_bf16_f32 v130, v172, v173
	v_cvt_pk_bf16_f32 v131, v174, v175
	v_cvt_pk_bf16_f32 v132, v176, v177
	v_cvt_pk_bf16_f32 v133, v178, v179
	v_cvt_pk_bf16_f32 v134, v180, v181
	v_cvt_pk_bf16_f32 v135, v182, v183
	v_cvt_pk_bf16_f32 v136, v184, v185
	v_cvt_pk_bf16_f32 v137, v186, v187
	v_mov_b32_e32 v140, v134
	v_mov_b32_e32 v141, v135
	v_mov_b32_e32 v142, v136
	v_mov_b32_e32 v143, v137
	v_mov_b32_dpp v134, v130 row_ror:8 row_mask:0xf bank_mask:0x3
	v_mov_b32_dpp v135, v131 row_ror:8 row_mask:0xf bank_mask:0x3
	v_mov_b32_dpp v136, v132 row_ror:8 row_mask:0xf bank_mask:0x3
	v_mov_b32_dpp v137, v133 row_ror:8 row_mask:0xf bank_mask:0x3
	v_mov_b32_dpp v130, v140 row_ror:8 row_mask:0xf bank_mask:0xc
	v_mov_b32_dpp v131, v141 row_ror:8 row_mask:0xf bank_mask:0xc
	v_mov_b32_dpp v132, v142 row_ror:8 row_mask:0xf bank_mask:0xc
	v_mov_b32_dpp v133, v143 row_ror:8 row_mask:0xf bank_mask:0xc
	global_store_dwordx4 v138, v[130:133], s[6:7] sc1 nt
	global_store_dwordx4 v139, v[134:137], s[6:7] sc1 nt
	s_add_u32 s6, s6, 0x8000
	s_addc_u32 s7, s7, 0
	v_pk_mul_f32 v[206:207], v[86:87], s[24:25] op_sel_hi:[1,0]
	v_pk_mul_f32 v[208:209], v[88:89], s[24:25] op_sel_hi:[1,0]
	v_pk_mul_f32 v[210:211], v[82:83], s[24:25] op_sel_hi:[1,0]
	v_pk_mul_f32 v[212:213], v[84:85], s[24:25] op_sel_hi:[1,0]
	v_exp_f32_e32 v206, v206
	v_exp_f32_e32 v207, v207
	v_exp_f32_e32 v208, v208
	v_exp_f32_e32 v209, v209
	v_exp_f32_e32 v210, v210
	v_exp_f32_e32 v211, v211
	v_exp_f32_e32 v212, v212
	v_exp_f32_e32 v213, v213
	v_pk_add_f32 v[206:207], v[206:207], 1.0 op_sel_hi:[1,0]
	v_pk_add_f32 v[208:209], v[208:209], 1.0 op_sel_hi:[1,0]
	v_pk_add_f32 v[210:211], v[210:211], 1.0 op_sel_hi:[1,0]
	v_pk_add_f32 v[212:213], v[212:213], 1.0 op_sel_hi:[1,0]
	v_rcp_f32_e32 v206, v206
	v_rcp_f32_e32 v207, v207
	v_rcp_f32_e32 v208, v208
	v_rcp_f32_e32 v209, v209
	v_rcp_f32_e32 v210, v210
	v_rcp_f32_e32 v211, v211
	v_rcp_f32_e32 v212, v212
	v_rcp_f32_e32 v213, v213
	v_pk_mul_f32 v[206:207], v[86:87], v[206:207]
	v_pk_mul_f32 v[208:209], v[88:89], v[208:209]
	v_pk_mul_f32 v[210:211], v[82:83], v[210:211]
	v_pk_mul_f32 v[212:213], v[84:85], v[212:213]
	v_pk_mul_f32 v[214:215], v[22:23], s[24:25] op_sel_hi:[1,0]
	v_pk_mul_f32 v[216:217], v[24:25], s[24:25] op_sel_hi:[1,0]
	v_pk_mul_f32 v[218:219], v[18:19], s[24:25] op_sel_hi:[1,0]
	v_pk_mul_f32 v[220:221], v[20:21], s[24:25] op_sel_hi:[1,0]
	v_exp_f32_e32 v214, v214
	v_exp_f32_e32 v215, v215
	v_exp_f32_e32 v216, v216
	v_exp_f32_e32 v217, v217
	v_exp_f32_e32 v218, v218
	v_exp_f32_e32 v219, v219
	v_exp_f32_e32 v220, v220
	v_exp_f32_e32 v221, v221
	v_pk_add_f32 v[214:215], v[214:215], 1.0 op_sel_hi:[1,0]
	v_pk_add_f32 v[216:217], v[216:217], 1.0 op_sel_hi:[1,0]
	v_pk_add_f32 v[218:219], v[218:219], 1.0 op_sel_hi:[1,0]
	v_pk_add_f32 v[220:221], v[220:221], 1.0 op_sel_hi:[1,0]
	v_rcp_f32_e32 v214, v214
	v_rcp_f32_e32 v215, v215
	v_rcp_f32_e32 v216, v216
	v_rcp_f32_e32 v217, v217
	v_rcp_f32_e32 v218, v218
	v_rcp_f32_e32 v219, v219
	v_rcp_f32_e32 v220, v220
	v_rcp_f32_e32 v221, v221
	v_pk_mul_f32 v[214:215], v[22:23], v[214:215]
	v_pk_mul_f32 v[216:217], v[24:25], v[216:217]
	v_pk_mul_f32 v[218:219], v[18:19], v[218:219]
	v_pk_mul_f32 v[220:221], v[20:21], v[220:221]
	v_cvt_pk_bf16_f32 v156, v206, v207
	v_cvt_pk_bf16_f32 v157, v208, v209
	v_cvt_pk_bf16_f32 v158, v210, v211
	v_cvt_pk_bf16_f32 v159, v212, v213
	v_cvt_pk_bf16_f32 v160, v214, v215
	v_cvt_pk_bf16_f32 v161, v216, v217
	v_cvt_pk_bf16_f32 v162, v218, v219
	v_cvt_pk_bf16_f32 v163, v220, v221
	v_mov_b32_e32 v188, v160
	v_mov_b32_e32 v189, v161
	v_mov_b32_e32 v190, v162
	v_mov_b32_e32 v191, v163
	v_mov_b32_dpp v160, v156 row_ror:8 row_mask:0xf bank_mask:0x3
	v_mov_b32_dpp v161, v157 row_ror:8 row_mask:0xf bank_mask:0x3
	v_mov_b32_dpp v162, v158 row_ror:8 row_mask:0xf bank_mask:0x3
	v_mov_b32_dpp v163, v159 row_ror:8 row_mask:0xf bank_mask:0x3
	v_mov_b32_dpp v156, v188 row_ror:8 row_mask:0xf bank_mask:0xc
	v_mov_b32_dpp v157, v189 row_ror:8 row_mask:0xf bank_mask:0xc
	v_mov_b32_dpp v158, v190 row_ror:8 row_mask:0xf bank_mask:0xc
	v_mov_b32_dpp v159, v191 row_ror:8 row_mask:0xf bank_mask:0xc
	global_store_dwordx4 v138, v[156:159], s[6:7] sc1 nt
	global_store_dwordx4 v139, v[160:163], s[6:7] sc1 nt
	s_add_u32 s6, s6, 0x8000
	s_addc_u32 s7, s7, 0
	v_pk_mul_f32 v[172:173], v[78:79], s[24:25] op_sel_hi:[1,0]
	v_pk_mul_f32 v[174:175], v[80:81], s[24:25] op_sel_hi:[1,0]
	v_pk_mul_f32 v[176:177], v[74:75], s[24:25] op_sel_hi:[1,0]
	v_pk_mul_f32 v[178:179], v[76:77], s[24:25] op_sel_hi:[1,0]
	v_exp_f32_e32 v172, v172
	v_exp_f32_e32 v173, v173
	v_exp_f32_e32 v174, v174
	v_exp_f32_e32 v175, v175
	v_exp_f32_e32 v176, v176
	v_exp_f32_e32 v177, v177
	v_exp_f32_e32 v178, v178
	v_exp_f32_e32 v179, v179
; __device__ __forceinline__ unsigned cvt_pk_bf16(float lo, float hi) { unsigned r; asm volatile("v_cvt_pk_bf16_f32 %0, %1, %2" : "=v"(r) : "v"(lo), "v"(hi)); return r; }
; __device__ __forceinline__ float sigm(float x) { return __builtin_amdgcn_rcpf(1.f + __expf(-x)); }
; __device__ __forceinline__ u32x4 pack8(const f32x4 v0, const f32x4 v1) { u32x4 w; w.x = cvt_pk_bf16(v0[0], v0[1]); w.y = cvt_pk_bf16(v0[2], v0[3]); w.z = cvt_pk_bf16(v1[0], v1[1]); w.w = cvt_pk_bf16(v1[2], v1[3]); return w; }
;     __device__ __forceinline__ void operator()(f32x4 (&acc)[2][2][4][2], const Unit& u, int wr, int wc, int fr, int fq) const {
;     ...
;             for (int ai = 0; ai < 2; ++ai)
; #pragma unroll
;                 for (int m = 0; m < 4; ++m) { bf16_t* rowp = base + (size_t)(ai * HALF + m * 16) * LDZ;
; #pragma unroll
;                     for (int bj = 0; bj < 2; ++bj) { f32x4 v0 = acc[ai][bj][m][0], v1 = acc[ai][bj][m][1];
;                         if (kind == 1) {
; #pragma unroll
;                             for (int e = 0; e < 4; ++e) { v0[e] = v0[e] * sigm(v0[e]); v1[e] = v1[e] * sigm(v1[e]); } }
;                         else if (kind == 2) { v0 = v0 * (0.125f * LOG2E); v1 = v1 * (0.125f * LOG2E); }
;                         else if (kind == 3) {
; #pragma unroll
;                             for (int e = 0; e < 4; ++e) { v0[e] = sigm(v0[e] + bv[bj][0][e]); v1[e] = sigm(v1[e] + bv[bj][1][e]); } }
;                         __builtin_nontemporal_store(pack8(v0, v1), (u32x4*)(rowp + bj * HALF)); } }
	v_pk_add_f32 v[172:173], v[172:173], 1.0 op_sel_hi:[1,0]
	v_pk_add_f32 v[174:175], v[174:175], 1.0 op_sel_hi:[1,0]
	v_pk_add_f32 v[176:177], v[176:177], 1.0 op_sel_hi:[1,0]
	v_pk_add_f32 v[178:179], v[178:179], 1.0 op_sel_hi:[1,0]
	v_rcp_f32_e32 v172, v172
	v_rcp_f32_e32 v173, v173
	v_rcp_f32_e32 v174, v174
	v_rcp_f32_e32 v175, v175
	v_rcp_f32_e32 v176, v176
	v_rcp_f32_e32 v177, v177
	v_rcp_f32_e32 v178, v178
	v_rcp_f32_e32 v179, v179
	v_pk_mul_f32 v[172:173], v[78:79], v[172:173]
	v_pk_mul_f32 v[174:175], v[80:81], v[174:175]
	v_pk_mul_f32 v[176:177], v[74:75], v[176:177]
	v_pk_mul_f32 v[178:179], v[76:77], v[178:179]
	v_pk_mul_f32 v[180:181], v[14:15], s[24:25] op_sel_hi:[1,0]
	v_pk_mul_f32 v[182:183], v[16:17], s[24:25] op_sel_hi:[1,0]
	v_pk_mul_f32 v[184:185], v[10:11], s[24:25] op_sel_hi:[1,0]
	v_pk_mul_f32 v[186:187], v[12:13], s[24:25] op_sel_hi:[1,0]
	v_exp_f32_e32 v180, v180
	v_exp_f32_e32 v181, v181
	v_exp_f32_e32 v182, v182
	v_exp_f32_e32 v183, v183
	v_exp_f32_e32 v184, v184
	v_exp_f32_e32 v185, v185
	v_exp_f32_e32 v186, v186
	v_exp_f32_e32 v187, v187
	v_pk_add_f32 v[180:181], v[180:181], 1.0 op_sel_hi:[1,0]
	v_pk_add_f32 v[182:183], v[182:183], 1.0 op_sel_hi:[1,0]
	v_pk_add_f32 v[184:185], v[184:185], 1.0 op_sel_hi:[1,0]
	v_pk_add_f32 v[186:187], v[186:187], 1.0 op_sel_hi:[1,0]
	v_rcp_f32_e32 v180, v180
	v_rcp_f32_e32 v181, v181
	v_rcp_f32_e32 v182, v182
	v_rcp_f32_e32 v183, v183
	v_rcp_f32_e32 v184, v184
	v_rcp_f32_e32 v185, v185
	v_rcp_f32_e32 v186, v186
	v_rcp_f32_e32 v187, v187
	v_pk_mul_f32 v[180:181], v[14:15], v[180:181]
	v_pk_mul_f32 v[182:183], v[16:17], v[182:183]
	v_pk_mul_f32 v[184:185], v[10:11], v[184:185]
	v_pk_mul_f32 v[186:187], v[12:13], v[186:187]
	v_cvt_pk_bf16_f32 v130, v172, v173
	v_cvt_pk_bf16_f32 v131, v174, v175
	v_cvt_pk_bf16_f32 v132, v176, v177
	v_cvt_pk_bf16_f32 v133, v178, v179
	v_cvt_pk_bf16_f32 v134, v180, v181
	v_cvt_pk_bf16_f32 v135, v182, v183
	v_cvt_pk_bf16_f32 v136, v184, v185
	v_cvt_pk_bf16_f32 v137, v186, v187
	v_mov_b32_e32 v140, v134
	v_mov_b32_e32 v141, v135
	v_mov_b32_e32 v142, v136
	v_mov_b32_e32 v143, v137
	v_mov_b32_dpp v134, v130 row_ror:8 row_mask:0xf bank_mask:0x3
	v_mov_b32_dpp v135, v131 row_ror:8 row_mask:0xf bank_mask:0x3
	v_mov_b32_dpp v136, v132 row_ror:8 row_mask:0xf bank_mask:0x3
	v_mov_b32_dpp v137, v133 row_ror:8 row_mask:0xf bank_mask:0x3
	v_mov_b32_dpp v130, v140 row_ror:8 row_mask:0xf bank_mask:0xc
	v_mov_b32_dpp v131, v141 row_ror:8 row_mask:0xf bank_mask:0xc
	v_mov_b32_dpp v132, v142 row_ror:8 row_mask:0xf bank_mask:0xc
	v_mov_b32_dpp v133, v143 row_ror:8 row_mask:0xf bank_mask:0xc
	global_store_dwordx4 v138, v[130:133], s[6:7] sc1 nt
	global_store_dwordx4 v139, v[134:137], s[6:7] sc1 nt
	s_add_u32 s6, s6, 0x8000
	s_addc_u32 s7, s7, 0
	v_pk_mul_f32 v[206:207], v[70:71], s[24:25] op_sel_hi:[1,0]
	v_pk_mul_f32 v[208:209], v[72:73], s[24:25] op_sel_hi:[1,0]
	v_pk_mul_f32 v[210:211], v[66:67], s[24:25] op_sel_hi:[1,0]
	v_pk_mul_f32 v[212:213], v[68:69], s[24:25] op_sel_hi:[1,0]
	v_exp_f32_e32 v206, v206
	v_exp_f32_e32 v207, v207
	v_exp_f32_e32 v208, v208
	v_exp_f32_e32 v209, v209
	v_exp_f32_e32 v210, v210
	v_exp_f32_e32 v211, v211
	v_exp_f32_e32 v212, v212
	v_exp_f32_e32 v213, v213
	v_pk_add_f32 v[206:207], v[206:207], 1.0 op_sel_hi:[1,0]
	v_pk_add_f32 v[208:209], v[208:209], 1.0 op_sel_hi:[1,0]
	v_pk_add_f32 v[210:211], v[210:211], 1.0 op_sel_hi:[1,0]
	v_pk_add_f32 v[212:213], v[212:213], 1.0 op_sel_hi:[1,0]
	v_rcp_f32_e32 v206, v206
	v_rcp_f32_e32 v207, v207
	v_rcp_f32_e32 v208, v208
	v_rcp_f32_e32 v209, v209
	v_rcp_f32_e32 v210, v210
	v_rcp_f32_e32 v211, v211
	v_rcp_f32_e32 v212, v212
	v_rcp_f32_e32 v213, v213
	v_pk_mul_f32 v[206:207], v[70:71], v[206:207]
	v_pk_mul_f32 v[208:209], v[72:73], v[208:209]
	v_pk_mul_f32 v[210:211], v[66:67], v[210:211]
	v_pk_mul_f32 v[212:213], v[68:69], v[212:213]
	v_pk_mul_f32 v[214:215], v[6:7], s[24:25] op_sel_hi:[1,0]
	v_pk_mul_f32 v[216:217], v[8:9], s[24:25] op_sel_hi:[1,0]
	v_pk_mul_f32 v[218:219], v[2:3], s[24:25] op_sel_hi:[1,0]
	v_pk_mul_f32 v[220:221], v[4:5], s[24:25] op_sel_hi:[1,0]
	v_exp_f32_e32 v214, v214
	v_exp_f32_e32 v215, v215
	v_exp_f32_e32 v216, v216
	v_exp_f32_e32 v217, v217
	v_exp_f32_e32 v218, v218
	v_exp_f32_e32 v219, v219
	v_exp_f32_e32 v220, v220
	v_exp_f32_e32 v221, v221
	v_pk_add_f32 v[214:215], v[214:215], 1.0 op_sel_hi:[1,0]
	v_pk_add_f32 v[216:217], v[216:217], 1.0 op_sel_hi:[1,0]
	v_pk_add_f32 v[218:219], v[218:219], 1.0 op_sel_hi:[1,0]
	v_pk_add_f32 v[220:221], v[220:221], 1.0 op_sel_hi:[1,0]
	v_rcp_f32_e32 v214, v214
	v_rcp_f32_e32 v215, v215
	v_rcp_f32_e32 v216, v216
	v_rcp_f32_e32 v217, v217
	v_rcp_f32_e32 v218, v218
	v_rcp_f32_e32 v219, v219
	v_rcp_f32_e32 v220, v220
	v_rcp_f32_e32 v221, v221
	v_pk_mul_f32 v[214:215], v[6:7], v[214:215]
	v_pk_mul_f32 v[216:217], v[8:9], v[216:217]
	v_pk_mul_f32 v[218:219], v[2:3], v[218:219]
	v_pk_mul_f32 v[220:221], v[4:5], v[220:221]
	v_cvt_pk_bf16_f32 v156, v206, v207
	v_cvt_pk_bf16_f32 v157, v208, v209
	v_cvt_pk_bf16_f32 v158, v210, v211
	v_cvt_pk_bf16_f32 v159, v212, v213
	v_cvt_pk_bf16_f32 v160, v214, v215
	v_cvt_pk_bf16_f32 v161, v216, v217
	v_cvt_pk_bf16_f32 v162, v218, v219
	v_cvt_pk_bf16_f32 v163, v220, v221
	v_mov_b32_e32 v188, v160
	v_mov_b32_e32 v189, v161
	v_mov_b32_e32 v190, v162
	v_mov_b32_e32 v191, v163
	v_mov_b32_dpp v160, v156 row_ror:8 row_mask:0xf bank_mask:0x3
	v_mov_b32_dpp v161, v157 row_ror:8 row_mask:0xf bank_mask:0x3
	v_mov_b32_dpp v162, v158 row_ror:8 row_mask:0xf bank_mask:0x3
	v_mov_b32_dpp v163, v159 row_ror:8 row_mask:0xf bank_mask:0x3
	v_mov_b32_dpp v156, v188 row_ror:8 row_mask:0xf bank_mask:0xc
	v_mov_b32_dpp v157, v189 row_ror:8 row_mask:0xf bank_mask:0xc
	v_mov_b32_dpp v158, v190 row_ror:8 row_mask:0xf bank_mask:0xc
	v_mov_b32_dpp v159, v191 row_ror:8 row_mask:0xf bank_mask:0xc
	global_store_dwordx4 v138, v[156:159], s[6:7] sc1 nt
	global_store_dwordx4 v139, v[160:163], s[6:7] sc1 nt
	s_branch .Lepi1_done
; __device__ __forceinline__ unsigned cvt_pk_bf16(float lo, float hi) { unsigned r; asm volatile("v_cvt_pk_bf16_f32 %0, %1, %2" : "=v"(r) : "v"(lo), "v"(hi)); return r; }
; __device__ __forceinline__ float sigm(float x) { return __builtin_amdgcn_rcpf(1.f + __expf(-x)); }
; __device__ __forceinline__ u32x4 pack8(const f32x4 v0, const f32x4 v1) { u32x4 w; w.x = cvt_pk_bf16(v0[0], v0[1]); w.y = cvt_pk_bf16(v0[2], v0[3]); w.z = cvt_pk_bf16(v1[0], v1[1]); w.w = cvt_pk_bf16(v1[2], v1[3]); return w; }
;     __device__ __forceinline__ void operator()(f32x4 (&acc)[2][2][4][2], const Unit& u, int wr, int wc, int fr, int fq) const {
;     ...
;             for (int ai = 0; ai < 2; ++ai)
; #pragma unroll
;                 for (int m = 0; m < 4; ++m) { bf16_t* rowp = base + (size_t)(ai * HALF + m * 16) * LDZ;
; #pragma unroll
;                     for (int bj = 0; bj < 2; ++bj) { f32x4 v0 = acc[ai][bj][m][0], v1 = acc[ai][bj][m][1];
;                         if (kind == 1) {
; #pragma unroll
;                             for (int e = 0; e < 4; ++e) { v0[e] = v0[e] * sigm(v0[e]); v1[e] = v1[e] * sigm(v1[e]); } }
;                         else if (kind == 2) { v0 = v0 * (0.125f * LOG2E); v1 = v1 * (0.125f * LOG2E); }
;                         else if (kind == 3) {
; #pragma unroll
;                             for (int e = 0; e < 4; ++e) { v0[e] = sigm(v0[e] + bv[bj][0][e]); v1[e] = sigm(v1[e] + bv[bj][1][e]); } }
;                         __builtin_nontemporal_store(pack8(v0, v1), (u32x4*)(rowp + bj * HALF)); } }
.Lepi1_k2:
	s_mov_b64 s[6:7], s[50:51]
	v_pk_mul_f32 v[172:173], v[126:127], s[26:27] op_sel_hi:[1,0]
	v_pk_mul_f32 v[174:175], v[128:129], s[26:27] op_sel_hi:[1,0]
	v_pk_mul_f32 v[176:177], v[122:123], s[26:27] op_sel_hi:[1,0]
	v_pk_mul_f32 v[178:179], v[124:125], s[26:27] op_sel_hi:[1,0]
	v_pk_mul_f32 v[180:181], v[62:63], s[26:27] op_sel_hi:[1,0]
	v_pk_mul_f32 v[182:183], v[64:65], s[26:27] op_sel_hi:[1,0]
	v_pk_mul_f32 v[184:185], v[58:59], s[26:27] op_sel_hi:[1,0]
	v_pk_mul_f32 v[186:187], v[60:61], s[26:27] op_sel_hi:[1,0]
	v_cvt_pk_bf16_f32 v130, v172, v173
	v_cvt_pk_bf16_f32 v131, v174, v175
	v_cvt_pk_bf16_f32 v132, v176, v177
	v_cvt_pk_bf16_f32 v133, v178, v179
	v_cvt_pk_bf16_f32 v134, v180, v181
	v_cvt_pk_bf16_f32 v135, v182, v183
	v_cvt_pk_bf16_f32 v136, v184, v185
	v_cvt_pk_bf16_f32 v137, v186, v187
	v_mov_b32_e32 v140, v134
	v_mov_b32_e32 v141, v135
	v_mov_b32_e32 v142, v136
	v_mov_b32_e32 v143, v137
	v_mov_b32_dpp v134, v130 row_ror:8 row_mask:0xf bank_mask:0x3
	v_mov_b32_dpp v135, v131 row_ror:8 row_mask:0xf bank_mask:0x3
	v_mov_b32_dpp v136, v132 row_ror:8 row_mask:0xf bank_mask:0x3
	v_mov_b32_dpp v137, v133 row_ror:8 row_mask:0xf bank_mask:0x3
	v_mov_b32_dpp v130, v140 row_ror:8 row_mask:0xf bank_mask:0xc
	v_mov_b32_dpp v131, v141 row_ror:8 row_mask:0xf bank_mask:0xc
	v_mov_b32_dpp v132, v142 row_ror:8 row_mask:0xf bank_mask:0xc
	v_mov_b32_dpp v133, v143 row_ror:8 row_mask:0xf bank_mask:0xc
	global_store_dwordx4 v138, v[130:133], s[6:7] sc1 nt
	global_store_dwordx4 v139, v[134:137], s[6:7] sc1 nt
	s_add_u32 s6, s6, 0x8000
	s_addc_u32 s7, s7, 0
	v_pk_mul_f32 v[206:207], v[118:119], s[26:27] op_sel_hi:[1,0]
	v_pk_mul_f32 v[208:209], v[120:121], s[26:27] op_sel_hi:[1,0]
	v_pk_mul_f32 v[210:211], v[114:115], s[26:27] op_sel_hi:[1,0]
	v_pk_mul_f32 v[212:213], v[116:117], s[26:27] op_sel_hi:[1,0]
	v_pk_mul_f32 v[214:215], v[54:55], s[26:27] op_sel_hi:[1,0]
	v_pk_mul_f32 v[216:217], v[56:57], s[26:27] op_sel_hi:[1,0]
	v_pk_mul_f32 v[218:219], v[50:51], s[26:27] op_sel_hi:[1,0]
	v_pk_mul_f32 v[220:221], v[52:53], s[26:27] op_sel_hi:[1,0]
	v_cvt_pk_bf16_f32 v156, v206, v207
	v_cvt_pk_bf16_f32 v157, v208, v209
	v_cvt_pk_bf16_f32 v158, v210, v211
	v_cvt_pk_bf16_f32 v159, v212, v213
	v_cvt_pk_bf16_f32 v160, v214, v215
	v_cvt_pk_bf16_f32 v161, v216, v217
	v_cvt_pk_bf16_f32 v162, v218, v219
	v_cvt_pk_bf16_f32 v163, v220, v221
	v_mov_b32_e32 v188, v160
	v_mov_b32_e32 v189, v161
	v_mov_b32_e32 v190, v162
	v_mov_b32_e32 v191, v163
	v_mov_b32_dpp v160, v156 row_ror:8 row_mask:0xf bank_mask:0x3
	v_mov_b32_dpp v161, v157 row_ror:8 row_mask:0xf bank_mask:0x3
	v_mov_b32_dpp v162, v158 row_ror:8 row_mask:0xf bank_mask:0x3
	v_mov_b32_dpp v163, v159 row_ror:8 row_mask:0xf bank_mask:0x3
	v_mov_b32_dpp v156, v188 row_ror:8 row_mask:0xf bank_mask:0xc
	v_mov_b32_dpp v157, v189 row_ror:8 row_mask:0xf bank_mask:0xc
	v_mov_b32_dpp v158, v190 row_ror:8 row_mask:0xf bank_mask:0xc
	v_mov_b32_dpp v159, v191 row_ror:8 row_mask:0xf bank_mask:0xc
	global_store_dwordx4 v138, v[156:159], s[6:7] sc1 nt
	global_store_dwordx4 v139, v[160:163], s[6:7] sc1 nt
	s_add_u32 s6, s6, 0x8000
	s_addc_u32 s7, s7, 0
	v_pk_mul_f32 v[172:173], v[110:111], s[26:27] op_sel_hi:[1,0]
	v_pk_mul_f32 v[174:175], v[112:113], s[26:27] op_sel_hi:[1,0]
	v_pk_mul_f32 v[176:177], v[106:107], s[26:27] op_sel_hi:[1,0]
	v_pk_mul_f32 v[178:179], v[108:109], s[26:27] op_sel_hi:[1,0]
	v_pk_mul_f32 v[180:181], v[46:47], s[26:27] op_sel_hi:[1,0]
	v_pk_mul_f32 v[182:183], v[48:49], s[26:27] op_sel_hi:[1,0]
	v_pk_mul_f32 v[184:185], v[42:43], s[26:27] op_sel_hi:[1,0]
	v_pk_mul_f32 v[186:187], v[44:45], s[26:27] op_sel_hi:[1,0]
	v_cvt_pk_bf16_f32 v130, v172, v173
	v_cvt_pk_bf16_f32 v131, v174, v175
	v_cvt_pk_bf16_f32 v132, v176, v177
	v_cvt_pk_bf16_f32 v133, v178, v179
	v_cvt_pk_bf16_f32 v134, v180, v181
	v_cvt_pk_bf16_f32 v135, v182, v183
	v_cvt_pk_bf16_f32 v136, v184, v185
	v_cvt_pk_bf16_f32 v137, v186, v187
	v_mov_b32_e32 v140, v134
	v_mov_b32_e32 v141, v135
	v_mov_b32_e32 v142, v136
	v_mov_b32_e32 v143, v137
	v_mov_b32_dpp v134, v130 row_ror:8 row_mask:0xf bank_mask:0x3
	v_mov_b32_dpp v135, v131 row_ror:8 row_mask:0xf bank_mask:0x3
	v_mov_b32_dpp v136, v132 row_ror:8 row_mask:0xf bank_mask:0x3
	v_mov_b32_dpp v137, v133 row_ror:8 row_mask:0xf bank_mask:0x3
	v_mov_b32_dpp v130, v140 row_ror:8 row_mask:0xf bank_mask:0xc
	v_mov_b32_dpp v131, v141 row_ror:8 row_mask:0xf bank_mask:0xc
	v_mov_b32_dpp v132, v142 row_ror:8 row_mask:0xf bank_mask:0xc
	v_mov_b32_dpp v133, v143 row_ror:8 row_mask:0xf bank_mask:0xc
	global_store_dwordx4 v138, v[130:133], s[6:7] sc1 nt
	global_store_dwordx4 v139, v[134:137], s[6:7] sc1 nt
	s_add_u32 s6, s6, 0x8000
	s_addc_u32 s7, s7, 0
	v_pk_mul_f32 v[206:207], v[102:103], s[26:27] op_sel_hi:[1,0]
	v_pk_mul_f32 v[208:209], v[104:105], s[26:27] op_sel_hi:[1,0]
	v_pk_mul_f32 v[210:211], v[98:99], s[26:27] op_sel_hi:[1,0]
	v_pk_mul_f32 v[212:213], v[100:101], s[26:27] op_sel_hi:[1,0]
	v_pk_mul_f32 v[214:215], v[38:39], s[26:27] op_sel_hi:[1,0]
	v_pk_mul_f32 v[216:217], v[40:41], s[26:27] op_sel_hi:[1,0]
	v_pk_mul_f32 v[218:219], v[34:35], s[26:27] op_sel_hi:[1,0]
	v_pk_mul_f32 v[220:221], v[36:37], s[26:27] op_sel_hi:[1,0]
	v_cvt_pk_bf16_f32 v156, v206, v207
	v_cvt_pk_bf16_f32 v157, v208, v209
	v_cvt_pk_bf16_f32 v158, v210, v211
	v_cvt_pk_bf16_f32 v159, v212, v213
	v_cvt_pk_bf16_f32 v160, v214, v215
	v_cvt_pk_bf16_f32 v161, v216, v217
	v_cvt_pk_bf16_f32 v162, v218, v219
	v_cvt_pk_bf16_f32 v163, v220, v221
	v_mov_b32_e32 v188, v160
	v_mov_b32_e32 v189, v161
	v_mov_b32_e32 v190, v162
	v_mov_b32_e32 v191, v163
	v_mov_b32_dpp v160, v156 row_ror:8 row_mask:0xf bank_mask:0x3
; __device__ __forceinline__ unsigned cvt_pk_bf16(float lo, float hi) { unsigned r; asm volatile("v_cvt_pk_bf16_f32 %0, %1, %2" : "=v"(r) : "v"(lo), "v"(hi)); return r; }
; __device__ __forceinline__ float sigm(float x) { return __builtin_amdgcn_rcpf(1.f + __expf(-x)); }
; __device__ __forceinline__ u32x4 pack8(const f32x4 v0, const f32x4 v1) { u32x4 w; w.x = cvt_pk_bf16(v0[0], v0[1]); w.y = cvt_pk_bf16(v0[2], v0[3]); w.z = cvt_pk_bf16(v1[0], v1[1]); w.w = cvt_pk_bf16(v1[2], v1[3]); return w; }
;     __device__ __forceinline__ void operator()(f32x4 (&acc)[2][2][4][2], const Unit& u, int wr, int wc, int fr, int fq) const {
;     ...
;             for (int ai = 0; ai < 2; ++ai)
; #pragma unroll
;                 for (int m = 0; m < 4; ++m) { bf16_t* rowp = base + (size_t)(ai * HALF + m * 16) * LDZ;
; #pragma unroll
;                     for (int bj = 0; bj < 2; ++bj) { f32x4 v0 = acc[ai][bj][m][0], v1 = acc[ai][bj][m][1];
;                         if (kind == 1) {
; #pragma unroll
;                             for (int e = 0; e < 4; ++e) { v0[e] = v0[e] * sigm(v0[e]); v1[e] = v1[e] * sigm(v1[e]); } }
;                         else if (kind == 2) { v0 = v0 * (0.125f * LOG2E); v1 = v1 * (0.125f * LOG2E); }
;                         else if (kind == 3) {
; #pragma unroll
;                             for (int e = 0; e < 4; ++e) { v0[e] = sigm(v0[e] + bv[bj][0][e]); v1[e] = sigm(v1[e] + bv[bj][1][e]); } }
;                         __builtin_nontemporal_store(pack8(v0, v1), (u32x4*)(rowp + bj * HALF)); } }
	v_mov_b32_dpp v161, v157 row_ror:8 row_mask:0xf bank_mask:0x3
	v_mov_b32_dpp v162, v158 row_ror:8 row_mask:0xf bank_mask:0x3
	v_mov_b32_dpp v163, v159 row_ror:8 row_mask:0xf bank_mask:0x3
	v_mov_b32_dpp v156, v188 row_ror:8 row_mask:0xf bank_mask:0xc
	v_mov_b32_dpp v157, v189 row_ror:8 row_mask:0xf bank_mask:0xc
	v_mov_b32_dpp v158, v190 row_ror:8 row_mask:0xf bank_mask:0xc
	v_mov_b32_dpp v159, v191 row_ror:8 row_mask:0xf bank_mask:0xc
	global_store_dwordx4 v138, v[156:159], s[6:7] sc1 nt
	global_store_dwordx4 v139, v[160:163], s[6:7] sc1 nt
	s_add_u32 s6, s6, 0x28000
	s_addc_u32 s7, s7, 0
	v_pk_mul_f32 v[172:173], v[94:95], s[26:27] op_sel_hi:[1,0]
	v_pk_mul_f32 v[174:175], v[96:97], s[26:27] op_sel_hi:[1,0]
	v_pk_mul_f32 v[176:177], v[90:91], s[26:27] op_sel_hi:[1,0]
	v_pk_mul_f32 v[178:179], v[92:93], s[26:27] op_sel_hi:[1,0]
	v_pk_mul_f32 v[180:181], v[30:31], s[26:27] op_sel_hi:[1,0]
	v_pk_mul_f32 v[182:183], v[32:33], s[26:27] op_sel_hi:[1,0]
	v_pk_mul_f32 v[184:185], v[26:27], s[26:27] op_sel_hi:[1,0]
	v_pk_mul_f32 v[186:187], v[28:29], s[26:27] op_sel_hi:[1,0]
	v_cvt_pk_bf16_f32 v130, v172, v173
	v_cvt_pk_bf16_f32 v131, v174, v175
	v_cvt_pk_bf16_f32 v132, v176, v177
	v_cvt_pk_bf16_f32 v133, v178, v179
	v_cvt_pk_bf16_f32 v134, v180, v181
	v_cvt_pk_bf16_f32 v135, v182, v183
	v_cvt_pk_bf16_f32 v136, v184, v185
	v_cvt_pk_bf16_f32 v137, v186, v187
	v_mov_b32_e32 v140, v134
	v_mov_b32_e32 v141, v135
	v_mov_b32_e32 v142, v136
	v_mov_b32_e32 v143, v137
	v_mov_b32_dpp v134, v130 row_ror:8 row_mask:0xf bank_mask:0x3
	v_mov_b32_dpp v135, v131 row_ror:8 row_mask:0xf bank_mask:0x3
	v_mov_b32_dpp v136, v132 row_ror:8 row_mask:0xf bank_mask:0x3
	v_mov_b32_dpp v137, v133 row_ror:8 row_mask:0xf bank_mask:0x3
	v_mov_b32_dpp v130, v140 row_ror:8 row_mask:0xf bank_mask:0xc
	v_mov_b32_dpp v131, v141 row_ror:8 row_mask:0xf bank_mask:0xc
	v_mov_b32_dpp v132, v142 row_ror:8 row_mask:0xf bank_mask:0xc
	v_mov_b32_dpp v133, v143 row_ror:8 row_mask:0xf bank_mask:0xc
	global_store_dwordx4 v138, v[130:133], s[6:7] sc1 nt
	global_store_dwordx4 v139, v[134:137], s[6:7] sc1 nt
	s_add_u32 s6, s6, 0x8000
	s_addc_u32 s7, s7, 0
	v_pk_mul_f32 v[206:207], v[86:87], s[26:27] op_sel_hi:[1,0]
	v_pk_mul_f32 v[208:209], v[88:89], s[26:27] op_sel_hi:[1,0]
	v_pk_mul_f32 v[210:211], v[82:83], s[26:27] op_sel_hi:[1,0]
	v_pk_mul_f32 v[212:213], v[84:85], s[26:27] op_sel_hi:[1,0]
	v_pk_mul_f32 v[214:215], v[22:23], s[26:27] op_sel_hi:[1,0]
	v_pk_mul_f32 v[216:217], v[24:25], s[26:27] op_sel_hi:[1,0]
	v_pk_mul_f32 v[218:219], v[18:19], s[26:27] op_sel_hi:[1,0]
	v_pk_mul_f32 v[220:221], v[20:21], s[26:27] op_sel_hi:[1,0]
	v_cvt_pk_bf16_f32 v156, v206, v207
	v_cvt_pk_bf16_f32 v157, v208, v209
	v_cvt_pk_bf16_f32 v158, v210, v211
	v_cvt_pk_bf16_f32 v159, v212, v213
	v_cvt_pk_bf16_f32 v160, v214, v215
	v_cvt_pk_bf16_f32 v161, v216, v217
	v_cvt_pk_bf16_f32 v162, v218, v219
	v_cvt_pk_bf16_f32 v163, v220, v221
	v_mov_b32_e32 v188, v160
	v_mov_b32_e32 v189, v161
	v_mov_b32_e32 v190, v162
	v_mov_b32_e32 v191, v163
	v_mov_b32_dpp v160, v156 row_ror:8 row_mask:0xf bank_mask:0x3
	v_mov_b32_dpp v161, v157 row_ror:8 row_mask:0xf bank_mask:0x3
	v_mov_b32_dpp v162, v158 row_ror:8 row_mask:0xf bank_mask:0x3
	v_mov_b32_dpp v163, v159 row_ror:8 row_mask:0xf bank_mask:0x3
	v_mov_b32_dpp v156, v188 row_ror:8 row_mask:0xf bank_mask:0xc
	v_mov_b32_dpp v157, v189 row_ror:8 row_mask:0xf bank_mask:0xc
	v_mov_b32_dpp v158, v190 row_ror:8 row_mask:0xf bank_mask:0xc
	v_mov_b32_dpp v159, v191 row_ror:8 row_mask:0xf bank_mask:0xc
	global_store_dwordx4 v138, v[156:159], s[6:7] sc1 nt
	global_store_dwordx4 v139, v[160:163], s[6:7] sc1 nt
	s_add_u32 s6, s6, 0x8000
	s_addc_u32 s7, s7, 0
	v_pk_mul_f32 v[172:173], v[78:79], s[26:27] op_sel_hi:[1,0]
	v_pk_mul_f32 v[174:175], v[80:81], s[26:27] op_sel_hi:[1,0]
	v_pk_mul_f32 v[176:177], v[74:75], s[26:27] op_sel_hi:[1,0]
	v_pk_mul_f32 v[178:179], v[76:77], s[26:27] op_sel_hi:[1,0]
	v_pk_mul_f32 v[180:181], v[14:15], s[26:27] op_sel_hi:[1,0]
	v_pk_mul_f32 v[182:183], v[16:17], s[26:27] op_sel_hi:[1,0]
	v_pk_mul_f32 v[184:185], v[10:11], s[26:27] op_sel_hi:[1,0]
	v_pk_mul_f32 v[186:187], v[12:13], s[26:27] op_sel_hi:[1,0]
	v_cvt_pk_bf16_f32 v130, v172, v173
	v_cvt_pk_bf16_f32 v131, v174, v175
	v_cvt_pk_bf16_f32 v132, v176, v177
	v_cvt_pk_bf16_f32 v133, v178, v179
	v_cvt_pk_bf16_f32 v134, v180, v181
	v_cvt_pk_bf16_f32 v135, v182, v183
	v_cvt_pk_bf16_f32 v136, v184, v185
	v_cvt_pk_bf16_f32 v137, v186, v187
	v_mov_b32_e32 v140, v134
	v_mov_b32_e32 v141, v135
	v_mov_b32_e32 v142, v136
	v_mov_b32_e32 v143, v137
	v_mov_b32_dpp v134, v130 row_ror:8 row_mask:0xf bank_mask:0x3
	v_mov_b32_dpp v135, v131 row_ror:8 row_mask:0xf bank_mask:0x3
	v_mov_b32_dpp v136, v132 row_ror:8 row_mask:0xf bank_mask:0x3
	v_mov_b32_dpp v137, v133 row_ror:8 row_mask:0xf bank_mask:0x3
	v_mov_b32_dpp v130, v140 row_ror:8 row_mask:0xf bank_mask:0xc
	v_mov_b32_dpp v131, v141 row_ror:8 row_mask:0xf bank_mask:0xc
	v_mov_b32_dpp v132, v142 row_ror:8 row_mask:0xf bank_mask:0xc
	v_mov_b32_dpp v133, v143 row_ror:8 row_mask:0xf bank_mask:0xc
	global_store_dwordx4 v138, v[130:133], s[6:7] sc1 nt
	global_store_dwordx4 v139, v[134:137], s[6:7] sc1 nt
	s_add_u32 s6, s6, 0x8000
	s_addc_u32 s7, s7, 0
	v_pk_mul_f32 v[206:207], v[70:71], s[26:27] op_sel_hi:[1,0]
	v_pk_mul_f32 v[208:209], v[72:73], s[26:27] op_sel_hi:[1,0]
	v_pk_mul_f32 v[210:211], v[66:67], s[26:27] op_sel_hi:[1,0]
	v_pk_mul_f32 v[212:213], v[68:69], s[26:27] op_sel_hi:[1,0]
	v_pk_mul_f32 v[214:215], v[6:7], s[26:27] op_sel_hi:[1,0]
	v_pk_mul_f32 v[216:217], v[8:9], s[26:27] op_sel_hi:[1,0]
	v_pk_mul_f32 v[218:219], v[2:3], s[26:27] op_sel_hi:[1,0]
	v_pk_mul_f32 v[220:221], v[4:5], s[26:27] op_sel_hi:[1,0]
	v_cvt_pk_bf16_f32 v156, v206, v207
	v_cvt_pk_bf16_f32 v157, v208, v209
	v_cvt_pk_bf16_f32 v158, v210, v211
	v_cvt_pk_bf16_f32 v159, v212, v213
	v_cvt_pk_bf16_f32 v160, v214, v215
	v_cvt_pk_bf16_f32 v161, v216, v217
	v_cvt_pk_bf16_f32 v162, v218, v219
	v_cvt_pk_bf16_f32 v163, v220, v221
	v_mov_b32_e32 v188, v160
	v_mov_b32_e32 v189, v161
	v_mov_b32_e32 v190, v162
	v_mov_b32_e32 v191, v163
	v_mov_b32_dpp v160, v156 row_ror:8 row_mask:0xf bank_mask:0x3
	v_mov_b32_dpp v161, v157 row_ror:8 row_mask:0xf bank_mask:0x3
	v_mov_b32_dpp v162, v158 row_ror:8 row_mask:0xf bank_mask:0x3
	v_mov_b32_dpp v163, v159 row_ror:8 row_mask:0xf bank_mask:0x3
	v_mov_b32_dpp v156, v188 row_ror:8 row_mask:0xf bank_mask:0xc
	v_mov_b32_dpp v157, v189 row_ror:8 row_mask:0xf bank_mask:0xc
	v_mov_b32_dpp v158, v190 row_ror:8 row_mask:0xf bank_mask:0xc
	v_mov_b32_dpp v159, v191 row_ror:8 row_mask:0xf bank_mask:0xc
	global_store_dwordx4 v138, v[156:159], s[6:7] sc1 nt
	global_store_dwordx4 v139, v[160:163], s[6:7] sc1 nt
	s_branch .Lepi1_done
; __device__ __forceinline__ unsigned cvt_pk_bf16(float lo, float hi) { unsigned r; asm volatile("v_cvt_pk_bf16_f32 %0, %1, %2" : "=v"(r) : "v"(lo), "v"(hi)); return r; }
; __device__ __forceinline__ float sigm(float x) { return __builtin_amdgcn_rcpf(1.f + __expf(-x)); }
; __device__ __forceinline__ u32x4 pack8(const f32x4 v0, const f32x4 v1) { u32x4 w; w.x = cvt_pk_bf16(v0[0], v0[1]); w.y = cvt_pk_bf16(v0[2], v0[3]); w.z = cvt_pk_bf16(v1[0], v1[1]); w.w = cvt_pk_bf16(v1[2], v1[3]); return w; }
;     __device__ __forceinline__ void operator()(f32x4 (&acc)[2][2][4][2], const Unit& u, int wr, int wc, int fr, int fq) const {
;     ...
;             for (int ai = 0; ai < 2; ++ai)
; #pragma unroll
;                 for (int m = 0; m < 4; ++m) { bf16_t* rowp = base + (size_t)(ai * HALF + m * 16) * LDZ;
; #pragma unroll
;                     for (int bj = 0; bj < 2; ++bj) { f32x4 v0 = acc[ai][bj][m][0], v1 = acc[ai][bj][m][1];
;                         if (kind == 1) {
; #pragma unroll
;                             for (int e = 0; e < 4; ++e) { v0[e] = v0[e] * sigm(v0[e]); v1[e] = v1[e] * sigm(v1[e]); } }
;                         else if (kind == 2) { v0 = v0 * (0.125f * LOG2E); v1 = v1 * (0.125f * LOG2E); }
;                         else if (kind == 3) {
; #pragma unroll
;                             for (int e = 0; e < 4; ++e) { v0[e] = sigm(v0[e] + bv[bj][0][e]); v1[e] = sigm(v1[e] + bv[bj][1][e]); } }
;                         __builtin_nontemporal_store(pack8(v0, v1), (u32x4*)(rowp + bj * HALF)); } }
.Lepi1_k3:
	s_mov_b64 s[6:7], s[50:51]
	v_pk_add_f32 v[172:173], v[126:127], v[222:223]
	v_pk_add_f32 v[174:175], v[128:129], v[224:225]
	v_pk_add_f32 v[176:177], v[122:123], v[226:227]
	v_pk_add_f32 v[178:179], v[124:125], v[228:229]
	v_pk_mul_f32 v[172:173], v[172:173], s[24:25] op_sel_hi:[1,0]
	v_pk_mul_f32 v[174:175], v[174:175], s[24:25] op_sel_hi:[1,0]
	v_pk_mul_f32 v[176:177], v[176:177], s[24:25] op_sel_hi:[1,0]
	v_pk_mul_f32 v[178:179], v[178:179], s[24:25] op_sel_hi:[1,0]
	v_exp_f32_e32 v172, v172
	v_exp_f32_e32 v173, v173
	v_exp_f32_e32 v174, v174
	v_exp_f32_e32 v175, v175
	v_exp_f32_e32 v176, v176
	v_exp_f32_e32 v177, v177
	v_exp_f32_e32 v178, v178
	v_exp_f32_e32 v179, v179
	v_pk_add_f32 v[172:173], v[172:173], 1.0 op_sel_hi:[1,0]
	v_pk_add_f32 v[174:175], v[174:175], 1.0 op_sel_hi:[1,0]
	v_pk_add_f32 v[176:177], v[176:177], 1.0 op_sel_hi:[1,0]
	v_pk_add_f32 v[178:179], v[178:179], 1.0 op_sel_hi:[1,0]
	v_rcp_f32_e32 v172, v172
	v_rcp_f32_e32 v173, v173
	v_rcp_f32_e32 v174, v174
	v_rcp_f32_e32 v175, v175
	v_rcp_f32_e32 v176, v176
	v_rcp_f32_e32 v177, v177
	v_rcp_f32_e32 v178, v178
	v_rcp_f32_e32 v179, v179
	v_pk_add_f32 v[180:181], v[62:63], v[238:239]
	v_pk_add_f32 v[182:183], v[64:65], v[240:241]
	v_pk_add_f32 v[184:185], v[58:59], v[242:243]
	v_pk_add_f32 v[186:187], v[60:61], v[244:245]
	v_pk_mul_f32 v[180:181], v[180:181], s[24:25] op_sel_hi:[1,0]
	v_pk_mul_f32 v[182:183], v[182:183], s[24:25] op_sel_hi:[1,0]
	v_pk_mul_f32 v[184:185], v[184:185], s[24:25] op_sel_hi:[1,0]
	v_pk_mul_f32 v[186:187], v[186:187], s[24:25] op_sel_hi:[1,0]
	v_exp_f32_e32 v180, v180
	v_exp_f32_e32 v181, v181
	v_exp_f32_e32 v182, v182
	v_exp_f32_e32 v183, v183
	v_exp_f32_e32 v184, v184
	v_exp_f32_e32 v185, v185
	v_exp_f32_e32 v186, v186
	v_exp_f32_e32 v187, v187
	v_pk_add_f32 v[180:181], v[180:181], 1.0 op_sel_hi:[1,0]
	v_pk_add_f32 v[182:183], v[182:183], 1.0 op_sel_hi:[1,0]
	v_pk_add_f32 v[184:185], v[184:185], 1.0 op_sel_hi:[1,0]
	v_pk_add_f32 v[186:187], v[186:187], 1.0 op_sel_hi:[1,0]
	v_rcp_f32_e32 v180, v180
	v_rcp_f32_e32 v181, v181
	v_rcp_f32_e32 v182, v182
	v_rcp_f32_e32 v183, v183
	v_rcp_f32_e32 v184, v184
	v_rcp_f32_e32 v185, v185
	v_rcp_f32_e32 v186, v186
	v_rcp_f32_e32 v187, v187
	v_cvt_pk_bf16_f32 v130, v172, v173
	v_cvt_pk_bf16_f32 v131, v174, v175
	v_cvt_pk_bf16_f32 v132, v176, v177
	v_cvt_pk_bf16_f32 v133, v178, v179
	v_cvt_pk_bf16_f32 v134, v180, v181
	v_cvt_pk_bf16_f32 v135, v182, v183
	v_cvt_pk_bf16_f32 v136, v184, v185
	v_cvt_pk_bf16_f32 v137, v186, v187
	v_mov_b32_e32 v140, v134
	v_mov_b32_e32 v141, v135
	v_mov_b32_e32 v142, v136
	v_mov_b32_e32 v143, v137
	v_mov_b32_dpp v134, v130 row_ror:8 row_mask:0xf bank_mask:0x3
	v_mov_b32_dpp v135, v131 row_ror:8 row_mask:0xf bank_mask:0x3
	v_mov_b32_dpp v136, v132 row_ror:8 row_mask:0xf bank_mask:0x3
	v_mov_b32_dpp v137, v133 row_ror:8 row_mask:0xf bank_mask:0x3
	v_mov_b32_dpp v130, v140 row_ror:8 row_mask:0xf bank_mask:0xc
	v_mov_b32_dpp v131, v141 row_ror:8 row_mask:0xf bank_mask:0xc
	v_mov_b32_dpp v132, v142 row_ror:8 row_mask:0xf bank_mask:0xc
	v_mov_b32_dpp v133, v143 row_ror:8 row_mask:0xf bank_mask:0xc
	global_store_dwordx4 v138, v[130:133], s[6:7] sc1 nt
	global_store_dwordx4 v139, v[134:137], s[6:7] sc1 nt
	s_add_u32 s6, s6, 0x8000
	s_addc_u32 s7, s7, 0
	v_pk_add_f32 v[206:207], v[118:119], v[222:223]
	v_pk_add_f32 v[208:209], v[120:121], v[224:225]
	v_pk_add_f32 v[210:211], v[114:115], v[226:227]
	v_pk_add_f32 v[212:213], v[116:117], v[228:229]
	v_pk_mul_f32 v[206:207], v[206:207], s[24:25] op_sel_hi:[1,0]
	v_pk_mul_f32 v[208:209], v[208:209], s[24:25] op_sel_hi:[1,0]
	v_pk_mul_f32 v[210:211], v[210:211], s[24:25] op_sel_hi:[1,0]
	v_pk_mul_f32 v[212:213], v[212:213], s[24:25] op_sel_hi:[1,0]
	v_exp_f32_e32 v206, v206
	v_exp_f32_e32 v207, v207
	v_exp_f32_e32 v208, v208
	v_exp_f32_e32 v209, v209
	v_exp_f32_e32 v210, v210
	v_exp_f32_e32 v211, v211
	v_exp_f32_e32 v212, v212
	v_exp_f32_e32 v213, v213
	v_pk_add_f32 v[206:207], v[206:207], 1.0 op_sel_hi:[1,0]
	v_pk_add_f32 v[208:209], v[208:209], 1.0 op_sel_hi:[1,0]
	v_pk_add_f32 v[210:211], v[210:211], 1.0 op_sel_hi:[1,0]
	v_pk_add_f32 v[212:213], v[212:213], 1.0 op_sel_hi:[1,0]
	v_rcp_f32_e32 v206, v206
	v_rcp_f32_e32 v207, v207
	v_rcp_f32_e32 v208, v208
	v_rcp_f32_e32 v209, v209
	v_rcp_f32_e32 v210, v210
	v_rcp_f32_e32 v211, v211
	v_rcp_f32_e32 v212, v212
	v_rcp_f32_e32 v213, v213
	v_pk_add_f32 v[214:215], v[54:55], v[238:239]
	v_pk_add_f32 v[216:217], v[56:57], v[240:241]
	v_pk_add_f32 v[218:219], v[50:51], v[242:243]
	v_pk_add_f32 v[220:221], v[52:53], v[244:245]
	v_pk_mul_f32 v[214:215], v[214:215], s[24:25] op_sel_hi:[1,0]
	v_pk_mul_f32 v[216:217], v[216:217], s[24:25] op_sel_hi:[1,0]
	v_pk_mul_f32 v[218:219], v[218:219], s[24:25] op_sel_hi:[1,0]
	v_pk_mul_f32 v[220:221], v[220:221], s[24:25] op_sel_hi:[1,0]
	v_exp_f32_e32 v214, v214
	v_exp_f32_e32 v215, v215
	v_exp_f32_e32 v216, v216
	v_exp_f32_e32 v217, v217
	v_exp_f32_e32 v218, v218
	v_exp_f32_e32 v219, v219
	v_exp_f32_e32 v220, v220
	v_exp_f32_e32 v221, v221
	v_pk_add_f32 v[214:215], v[214:215], 1.0 op_sel_hi:[1,0]
	v_pk_add_f32 v[216:217], v[216:217], 1.0 op_sel_hi:[1,0]
	v_pk_add_f32 v[218:219], v[218:219], 1.0 op_sel_hi:[1,0]
	v_pk_add_f32 v[220:221], v[220:221], 1.0 op_sel_hi:[1,0]
	v_rcp_f32_e32 v214, v214
	v_rcp_f32_e32 v215, v215
	v_rcp_f32_e32 v216, v216
	v_rcp_f32_e32 v217, v217
	v_rcp_f32_e32 v218, v218
	v_rcp_f32_e32 v219, v219
	v_rcp_f32_e32 v220, v220
	v_rcp_f32_e32 v221, v221
	v_cvt_pk_bf16_f32 v156, v206, v207
	v_cvt_pk_bf16_f32 v157, v208, v209
	v_cvt_pk_bf16_f32 v158, v210, v211
	v_cvt_pk_bf16_f32 v159, v212, v213
	v_cvt_pk_bf16_f32 v160, v214, v215
; __device__ __forceinline__ unsigned cvt_pk_bf16(float lo, float hi) { unsigned r; asm volatile("v_cvt_pk_bf16_f32 %0, %1, %2" : "=v"(r) : "v"(lo), "v"(hi)); return r; }
; __device__ __forceinline__ float sigm(float x) { return __builtin_amdgcn_rcpf(1.f + __expf(-x)); }
; __device__ __forceinline__ u32x4 pack8(const f32x4 v0, const f32x4 v1) { u32x4 w; w.x = cvt_pk_bf16(v0[0], v0[1]); w.y = cvt_pk_bf16(v0[2], v0[3]); w.z = cvt_pk_bf16(v1[0], v1[1]); w.w = cvt_pk_bf16(v1[2], v1[3]); return w; }
;     __device__ __forceinline__ void operator()(f32x4 (&acc)[2][2][4][2], const Unit& u, int wr, int wc, int fr, int fq) const {
;     ...
;             for (int ai = 0; ai < 2; ++ai)
; #pragma unroll
;                 for (int m = 0; m < 4; ++m) { bf16_t* rowp = base + (size_t)(ai * HALF + m * 16) * LDZ;
; #pragma unroll
;                     for (int bj = 0; bj < 2; ++bj) { f32x4 v0 = acc[ai][bj][m][0], v1 = acc[ai][bj][m][1];
;                         if (kind == 1) {
; #pragma unroll
;                             for (int e = 0; e < 4; ++e) { v0[e] = v0[e] * sigm(v0[e]); v1[e] = v1[e] * sigm(v1[e]); } }
;                         else if (kind == 2) { v0 = v0 * (0.125f * LOG2E); v1 = v1 * (0.125f * LOG2E); }
;                         else if (kind == 3) {
; #pragma unroll
;                             for (int e = 0; e < 4; ++e) { v0[e] = sigm(v0[e] + bv[bj][0][e]); v1[e] = sigm(v1[e] + bv[bj][1][e]); } }
;                         __builtin_nontemporal_store(pack8(v0, v1), (u32x4*)(rowp + bj * HALF)); } }
	v_cvt_pk_bf16_f32 v161, v216, v217
	v_cvt_pk_bf16_f32 v162, v218, v219
	v_cvt_pk_bf16_f32 v163, v220, v221
	v_mov_b32_e32 v188, v160
	v_mov_b32_e32 v189, v161
	v_mov_b32_e32 v190, v162
	v_mov_b32_e32 v191, v163
	v_mov_b32_dpp v160, v156 row_ror:8 row_mask:0xf bank_mask:0x3
	v_mov_b32_dpp v161, v157 row_ror:8 row_mask:0xf bank_mask:0x3
	v_mov_b32_dpp v162, v158 row_ror:8 row_mask:0xf bank_mask:0x3
	v_mov_b32_dpp v163, v159 row_ror:8 row_mask:0xf bank_mask:0x3
	v_mov_b32_dpp v156, v188 row_ror:8 row_mask:0xf bank_mask:0xc
	v_mov_b32_dpp v157, v189 row_ror:8 row_mask:0xf bank_mask:0xc
	v_mov_b32_dpp v158, v190 row_ror:8 row_mask:0xf bank_mask:0xc
	v_mov_b32_dpp v159, v191 row_ror:8 row_mask:0xf bank_mask:0xc
	global_store_dwordx4 v138, v[156:159], s[6:7] sc1 nt
	global_store_dwordx4 v139, v[160:163], s[6:7] sc1 nt
	s_add_u32 s6, s6, 0x8000
	s_addc_u32 s7, s7, 0
	v_pk_add_f32 v[172:173], v[110:111], v[222:223]
	v_pk_add_f32 v[174:175], v[112:113], v[224:225]
	v_pk_add_f32 v[176:177], v[106:107], v[226:227]
	v_pk_add_f32 v[178:179], v[108:109], v[228:229]
	v_pk_mul_f32 v[172:173], v[172:173], s[24:25] op_sel_hi:[1,0]
	v_pk_mul_f32 v[174:175], v[174:175], s[24:25] op_sel_hi:[1,0]
	v_pk_mul_f32 v[176:177], v[176:177], s[24:25] op_sel_hi:[1,0]
	v_pk_mul_f32 v[178:179], v[178:179], s[24:25] op_sel_hi:[1,0]
	v_exp_f32_e32 v172, v172
	v_exp_f32_e32 v173, v173
	v_exp_f32_e32 v174, v174
	v_exp_f32_e32 v175, v175
	v_exp_f32_e32 v176, v176
	v_exp_f32_e32 v177, v177
	v_exp_f32_e32 v178, v178
	v_exp_f32_e32 v179, v179
	v_pk_add_f32 v[172:173], v[172:173], 1.0 op_sel_hi:[1,0]
	v_pk_add_f32 v[174:175], v[174:175], 1.0 op_sel_hi:[1,0]
	v_pk_add_f32 v[176:177], v[176:177], 1.0 op_sel_hi:[1,0]
	v_pk_add_f32 v[178:179], v[178:179], 1.0 op_sel_hi:[1,0]
	v_rcp_f32_e32 v172, v172
	v_rcp_f32_e32 v173, v173
	v_rcp_f32_e32 v174, v174
	v_rcp_f32_e32 v175, v175
	v_rcp_f32_e32 v176, v176
	v_rcp_f32_e32 v177, v177
	v_rcp_f32_e32 v178, v178
	v_rcp_f32_e32 v179, v179
	v_pk_add_f32 v[180:181], v[46:47], v[238:239]
	v_pk_add_f32 v[182:183], v[48:49], v[240:241]
	v_pk_add_f32 v[184:185], v[42:43], v[242:243]
	v_pk_add_f32 v[186:187], v[44:45], v[244:245]
	v_pk_mul_f32 v[180:181], v[180:181], s[24:25] op_sel_hi:[1,0]
	v_pk_mul_f32 v[182:183], v[182:183], s[24:25] op_sel_hi:[1,0]
	v_pk_mul_f32 v[184:185], v[184:185], s[24:25] op_sel_hi:[1,0]
	v_pk_mul_f32 v[186:187], v[186:187], s[24:25] op_sel_hi:[1,0]
	v_exp_f32_e32 v180, v180
	v_exp_f32_e32 v181, v181
	v_exp_f32_e32 v182, v182
	v_exp_f32_e32 v183, v183
	v_exp_f32_e32 v184, v184
	v_exp_f32_e32 v185, v185
	v_exp_f32_e32 v186, v186
	v_exp_f32_e32 v187, v187
	v_pk_add_f32 v[180:181], v[180:181], 1.0 op_sel_hi:[1,0]
	v_pk_add_f32 v[182:183], v[182:183], 1.0 op_sel_hi:[1,0]
	v_pk_add_f32 v[184:185], v[184:185], 1.0 op_sel_hi:[1,0]
	v_pk_add_f32 v[186:187], v[186:187], 1.0 op_sel_hi:[1,0]
	v_rcp_f32_e32 v180, v180
	v_rcp_f32_e32 v181, v181
	v_rcp_f32_e32 v182, v182
	v_rcp_f32_e32 v183, v183
	v_rcp_f32_e32 v184, v184
	v_rcp_f32_e32 v185, v185
	v_rcp_f32_e32 v186, v186
	v_rcp_f32_e32 v187, v187
	v_cvt_pk_bf16_f32 v130, v172, v173
	v_cvt_pk_bf16_f32 v131, v174, v175
	v_cvt_pk_bf16_f32 v132, v176, v177
	v_cvt_pk_bf16_f32 v133, v178, v179
	v_cvt_pk_bf16_f32 v134, v180, v181
	v_cvt_pk_bf16_f32 v135, v182, v183
	v_cvt_pk_bf16_f32 v136, v184, v185
	v_cvt_pk_bf16_f32 v137, v186, v187
	v_mov_b32_e32 v140, v134
	v_mov_b32_e32 v141, v135
	v_mov_b32_e32 v142, v136
	v_mov_b32_e32 v143, v137
	v_mov_b32_dpp v134, v130 row_ror:8 row_mask:0xf bank_mask:0x3
	v_mov_b32_dpp v135, v131 row_ror:8 row_mask:0xf bank_mask:0x3
	v_mov_b32_dpp v136, v132 row_ror:8 row_mask:0xf bank_mask:0x3
	v_mov_b32_dpp v137, v133 row_ror:8 row_mask:0xf bank_mask:0x3
	v_mov_b32_dpp v130, v140 row_ror:8 row_mask:0xf bank_mask:0xc
	v_mov_b32_dpp v131, v141 row_ror:8 row_mask:0xf bank_mask:0xc
	v_mov_b32_dpp v132, v142 row_ror:8 row_mask:0xf bank_mask:0xc
	v_mov_b32_dpp v133, v143 row_ror:8 row_mask:0xf bank_mask:0xc
	global_store_dwordx4 v138, v[130:133], s[6:7] sc1 nt
	global_store_dwordx4 v139, v[134:137], s[6:7] sc1 nt
	s_add_u32 s6, s6, 0x8000
	s_addc_u32 s7, s7, 0
	v_pk_add_f32 v[206:207], v[102:103], v[222:223]
	v_pk_add_f32 v[208:209], v[104:105], v[224:225]
	v_pk_add_f32 v[210:211], v[98:99], v[226:227]
	v_pk_add_f32 v[212:213], v[100:101], v[228:229]
	v_pk_mul_f32 v[206:207], v[206:207], s[24:25] op_sel_hi:[1,0]
	v_pk_mul_f32 v[208:209], v[208:209], s[24:25] op_sel_hi:[1,0]
	v_pk_mul_f32 v[210:211], v[210:211], s[24:25] op_sel_hi:[1,0]
	v_pk_mul_f32 v[212:213], v[212:213], s[24:25] op_sel_hi:[1,0]
	v_exp_f32_e32 v206, v206
	v_exp_f32_e32 v207, v207
	v_exp_f32_e32 v208, v208
	v_exp_f32_e32 v209, v209
	v_exp_f32_e32 v210, v210
	v_exp_f32_e32 v211, v211
	v_exp_f32_e32 v212, v212
	v_exp_f32_e32 v213, v213
	v_pk_add_f32 v[206:207], v[206:207], 1.0 op_sel_hi:[1,0]
	v_pk_add_f32 v[208:209], v[208:209], 1.0 op_sel_hi:[1,0]
	v_pk_add_f32 v[210:211], v[210:211], 1.0 op_sel_hi:[1,0]
	v_pk_add_f32 v[212:213], v[212:213], 1.0 op_sel_hi:[1,0]
	v_rcp_f32_e32 v206, v206
	v_rcp_f32_e32 v207, v207
	v_rcp_f32_e32 v208, v208
	v_rcp_f32_e32 v209, v209
	v_rcp_f32_e32 v210, v210
	v_rcp_f32_e32 v211, v211
	v_rcp_f32_e32 v212, v212
	v_rcp_f32_e32 v213, v213
	v_pk_add_f32 v[214:215], v[38:39], v[238:239]
	v_pk_add_f32 v[216:217], v[40:41], v[240:241]
	v_pk_add_f32 v[218:219], v[34:35], v[242:243]
	v_pk_add_f32 v[220:221], v[36:37], v[244:245]
	v_pk_mul_f32 v[214:215], v[214:215], s[24:25] op_sel_hi:[1,0]
	v_pk_mul_f32 v[216:217], v[216:217], s[24:25] op_sel_hi:[1,0]
	v_pk_mul_f32 v[218:219], v[218:219], s[24:25] op_sel_hi:[1,0]
	v_pk_mul_f32 v[220:221], v[220:221], s[24:25] op_sel_hi:[1,0]
; __device__ __forceinline__ unsigned cvt_pk_bf16(float lo, float hi) { unsigned r; asm volatile("v_cvt_pk_bf16_f32 %0, %1, %2" : "=v"(r) : "v"(lo), "v"(hi)); return r; }
; __device__ __forceinline__ float sigm(float x) { return __builtin_amdgcn_rcpf(1.f + __expf(-x)); }
; __device__ __forceinline__ u32x4 pack8(const f32x4 v0, const f32x4 v1) { u32x4 w; w.x = cvt_pk_bf16(v0[0], v0[1]); w.y = cvt_pk_bf16(v0[2], v0[3]); w.z = cvt_pk_bf16(v1[0], v1[1]); w.w = cvt_pk_bf16(v1[2], v1[3]); return w; }
;     __device__ __forceinline__ void operator()(f32x4 (&acc)[2][2][4][2], const Unit& u, int wr, int wc, int fr, int fq) const {
;     ...
;             for (int ai = 0; ai < 2; ++ai)
; #pragma unroll
;                 for (int m = 0; m < 4; ++m) { bf16_t* rowp = base + (size_t)(ai * HALF + m * 16) * LDZ;
; #pragma unroll
;                     for (int bj = 0; bj < 2; ++bj) { f32x4 v0 = acc[ai][bj][m][0], v1 = acc[ai][bj][m][1];
;                         if (kind == 1) {
; #pragma unroll
;                             for (int e = 0; e < 4; ++e) { v0[e] = v0[e] * sigm(v0[e]); v1[e] = v1[e] * sigm(v1[e]); } }
;                         else if (kind == 2) { v0 = v0 * (0.125f * LOG2E); v1 = v1 * (0.125f * LOG2E); }
;                         else if (kind == 3) {
; #pragma unroll
;                             for (int e = 0; e < 4; ++e) { v0[e] = sigm(v0[e] + bv[bj][0][e]); v1[e] = sigm(v1[e] + bv[bj][1][e]); } }
;                         __builtin_nontemporal_store(pack8(v0, v1), (u32x4*)(rowp + bj * HALF)); } }
	v_exp_f32_e32 v214, v214
	v_exp_f32_e32 v215, v215
	v_exp_f32_e32 v216, v216
	v_exp_f32_e32 v217, v217
	v_exp_f32_e32 v218, v218
	v_exp_f32_e32 v219, v219
	v_exp_f32_e32 v220, v220
	v_exp_f32_e32 v221, v221
	v_pk_add_f32 v[214:215], v[214:215], 1.0 op_sel_hi:[1,0]
	v_pk_add_f32 v[216:217], v[216:217], 1.0 op_sel_hi:[1,0]
	v_pk_add_f32 v[218:219], v[218:219], 1.0 op_sel_hi:[1,0]
	v_pk_add_f32 v[220:221], v[220:221], 1.0 op_sel_hi:[1,0]
	v_rcp_f32_e32 v214, v214
	v_rcp_f32_e32 v215, v215
	v_rcp_f32_e32 v216, v216
	v_rcp_f32_e32 v217, v217
	v_rcp_f32_e32 v218, v218
	v_rcp_f32_e32 v219, v219
	v_rcp_f32_e32 v220, v220
	v_rcp_f32_e32 v221, v221
	v_cvt_pk_bf16_f32 v156, v206, v207
	v_cvt_pk_bf16_f32 v157, v208, v209
	v_cvt_pk_bf16_f32 v158, v210, v211
	v_cvt_pk_bf16_f32 v159, v212, v213
	v_cvt_pk_bf16_f32 v160, v214, v215
	v_cvt_pk_bf16_f32 v161, v216, v217
	v_cvt_pk_bf16_f32 v162, v218, v219
	v_cvt_pk_bf16_f32 v163, v220, v221
	v_mov_b32_e32 v188, v160
	v_mov_b32_e32 v189, v161
	v_mov_b32_e32 v190, v162
	v_mov_b32_e32 v191, v163
	v_mov_b32_dpp v160, v156 row_ror:8 row_mask:0xf bank_mask:0x3
	v_mov_b32_dpp v161, v157 row_ror:8 row_mask:0xf bank_mask:0x3
	v_mov_b32_dpp v162, v158 row_ror:8 row_mask:0xf bank_mask:0x3
	v_mov_b32_dpp v163, v159 row_ror:8 row_mask:0xf bank_mask:0x3
	v_mov_b32_dpp v156, v188 row_ror:8 row_mask:0xf bank_mask:0xc
	v_mov_b32_dpp v157, v189 row_ror:8 row_mask:0xf bank_mask:0xc
	v_mov_b32_dpp v158, v190 row_ror:8 row_mask:0xf bank_mask:0xc
	v_mov_b32_dpp v159, v191 row_ror:8 row_mask:0xf bank_mask:0xc
	global_store_dwordx4 v138, v[156:159], s[6:7] sc1 nt
	global_store_dwordx4 v139, v[160:163], s[6:7] sc1 nt
	s_add_u32 s6, s6, 0x28000
	s_addc_u32 s7, s7, 0
	v_pk_add_f32 v[172:173], v[94:95], v[222:223]
	v_pk_add_f32 v[174:175], v[96:97], v[224:225]
	v_pk_add_f32 v[176:177], v[90:91], v[226:227]
	v_pk_add_f32 v[178:179], v[92:93], v[228:229]
	v_pk_mul_f32 v[172:173], v[172:173], s[24:25] op_sel_hi:[1,0]
	v_pk_mul_f32 v[174:175], v[174:175], s[24:25] op_sel_hi:[1,0]
	v_pk_mul_f32 v[176:177], v[176:177], s[24:25] op_sel_hi:[1,0]
	v_pk_mul_f32 v[178:179], v[178:179], s[24:25] op_sel_hi:[1,0]
	v_exp_f32_e32 v172, v172
	v_exp_f32_e32 v173, v173
	v_exp_f32_e32 v174, v174
	v_exp_f32_e32 v175, v175
	v_exp_f32_e32 v176, v176
	v_exp_f32_e32 v177, v177
	v_exp_f32_e32 v178, v178
	v_exp_f32_e32 v179, v179
	v_pk_add_f32 v[172:173], v[172:173], 1.0 op_sel_hi:[1,0]
	v_pk_add_f32 v[174:175], v[174:175], 1.0 op_sel_hi:[1,0]
	v_pk_add_f32 v[176:177], v[176:177], 1.0 op_sel_hi:[1,0]
	v_pk_add_f32 v[178:179], v[178:179], 1.0 op_sel_hi:[1,0]
	v_rcp_f32_e32 v172, v172
	v_rcp_f32_e32 v173, v173
	v_rcp_f32_e32 v174, v174
	v_rcp_f32_e32 v175, v175
	v_rcp_f32_e32 v176, v176
	v_rcp_f32_e32 v177, v177
	v_rcp_f32_e32 v178, v178
	v_rcp_f32_e32 v179, v179
	v_pk_add_f32 v[180:181], v[30:31], v[238:239]
	v_pk_add_f32 v[182:183], v[32:33], v[240:241]
	v_pk_add_f32 v[184:185], v[26:27], v[242:243]
	v_pk_add_f32 v[186:187], v[28:29], v[244:245]
	v_pk_mul_f32 v[180:181], v[180:181], s[24:25] op_sel_hi:[1,0]
	v_pk_mul_f32 v[182:183], v[182:183], s[24:25] op_sel_hi:[1,0]
	v_pk_mul_f32 v[184:185], v[184:185], s[24:25] op_sel_hi:[1,0]
	v_pk_mul_f32 v[186:187], v[186:187], s[24:25] op_sel_hi:[1,0]
	v_exp_f32_e32 v180, v180
	v_exp_f32_e32 v181, v181
	v_exp_f32_e32 v182, v182
	v_exp_f32_e32 v183, v183
	v_exp_f32_e32 v184, v184
	v_exp_f32_e32 v185, v185
	v_exp_f32_e32 v186, v186
	v_exp_f32_e32 v187, v187
	v_pk_add_f32 v[180:181], v[180:181], 1.0 op_sel_hi:[1,0]
	v_pk_add_f32 v[182:183], v[182:183], 1.0 op_sel_hi:[1,0]
	v_pk_add_f32 v[184:185], v[184:185], 1.0 op_sel_hi:[1,0]
	v_pk_add_f32 v[186:187], v[186:187], 1.0 op_sel_hi:[1,0]
	v_rcp_f32_e32 v180, v180
	v_rcp_f32_e32 v181, v181
	v_rcp_f32_e32 v182, v182
	v_rcp_f32_e32 v183, v183
	v_rcp_f32_e32 v184, v184
	v_rcp_f32_e32 v185, v185
	v_rcp_f32_e32 v186, v186
	v_rcp_f32_e32 v187, v187
	v_cvt_pk_bf16_f32 v130, v172, v173
	v_cvt_pk_bf16_f32 v131, v174, v175
	v_cvt_pk_bf16_f32 v132, v176, v177
	v_cvt_pk_bf16_f32 v133, v178, v179
	v_cvt_pk_bf16_f32 v134, v180, v181
	v_cvt_pk_bf16_f32 v135, v182, v183
	v_cvt_pk_bf16_f32 v136, v184, v185
	v_cvt_pk_bf16_f32 v137, v186, v187
	v_mov_b32_e32 v140, v134
	v_mov_b32_e32 v141, v135
	v_mov_b32_e32 v142, v136
	v_mov_b32_e32 v143, v137
	v_mov_b32_dpp v134, v130 row_ror:8 row_mask:0xf bank_mask:0x3
	v_mov_b32_dpp v135, v131 row_ror:8 row_mask:0xf bank_mask:0x3
	v_mov_b32_dpp v136, v132 row_ror:8 row_mask:0xf bank_mask:0x3
	v_mov_b32_dpp v137, v133 row_ror:8 row_mask:0xf bank_mask:0x3
	v_mov_b32_dpp v130, v140 row_ror:8 row_mask:0xf bank_mask:0xc
	v_mov_b32_dpp v131, v141 row_ror:8 row_mask:0xf bank_mask:0xc
	v_mov_b32_dpp v132, v142 row_ror:8 row_mask:0xf bank_mask:0xc
	v_mov_b32_dpp v133, v143 row_ror:8 row_mask:0xf bank_mask:0xc
	global_store_dwordx4 v138, v[130:133], s[6:7] sc1 nt
	global_store_dwordx4 v139, v[134:137], s[6:7] sc1 nt
	s_add_u32 s6, s6, 0x8000
	s_addc_u32 s7, s7, 0
	v_pk_add_f32 v[206:207], v[86:87], v[222:223]
	v_pk_add_f32 v[208:209], v[88:89], v[224:225]
	v_pk_add_f32 v[210:211], v[82:83], v[226:227]
	v_pk_add_f32 v[212:213], v[84:85], v[228:229]
	v_pk_mul_f32 v[206:207], v[206:207], s[24:25] op_sel_hi:[1,0]
	v_pk_mul_f32 v[208:209], v[208:209], s[24:25] op_sel_hi:[1,0]
	v_pk_mul_f32 v[210:211], v[210:211], s[24:25] op_sel_hi:[1,0]
	v_pk_mul_f32 v[212:213], v[212:213], s[24:25] op_sel_hi:[1,0]
	v_exp_f32_e32 v206, v206
	v_exp_f32_e32 v207, v207
	v_exp_f32_e32 v208, v208
	v_exp_f32_e32 v209, v209
	v_exp_f32_e32 v210, v210
	v_exp_f32_e32 v211, v211
	v_exp_f32_e32 v212, v212
	v_exp_f32_e32 v213, v213
	v_pk_add_f32 v[206:207], v[206:207], 1.0 op_sel_hi:[1,0]
; __device__ __forceinline__ unsigned cvt_pk_bf16(float lo, float hi) { unsigned r; asm volatile("v_cvt_pk_bf16_f32 %0, %1, %2" : "=v"(r) : "v"(lo), "v"(hi)); return r; }
; __device__ __forceinline__ float sigm(float x) { return __builtin_amdgcn_rcpf(1.f + __expf(-x)); }
; __device__ __forceinline__ u32x4 pack8(const f32x4 v0, const f32x4 v1) { u32x4 w; w.x = cvt_pk_bf16(v0[0], v0[1]); w.y = cvt_pk_bf16(v0[2], v0[3]); w.z = cvt_pk_bf16(v1[0], v1[1]); w.w = cvt_pk_bf16(v1[2], v1[3]); return w; }
;     __device__ __forceinline__ void operator()(f32x4 (&acc)[2][2][4][2], const Unit& u, int wr, int wc, int fr, int fq) const {
;     ...
;             for (int ai = 0; ai < 2; ++ai)
; #pragma unroll
;                 for (int m = 0; m < 4; ++m) { bf16_t* rowp = base + (size_t)(ai * HALF + m * 16) * LDZ;
; #pragma unroll
;                     for (int bj = 0; bj < 2; ++bj) { f32x4 v0 = acc[ai][bj][m][0], v1 = acc[ai][bj][m][1];
;                         if (kind == 1) {
; #pragma unroll
;                             for (int e = 0; e < 4; ++e) { v0[e] = v0[e] * sigm(v0[e]); v1[e] = v1[e] * sigm(v1[e]); } }
;                         else if (kind == 2) { v0 = v0 * (0.125f * LOG2E); v1 = v1 * (0.125f * LOG2E); }
;                         else if (kind == 3) {
; #pragma unroll
;                             for (int e = 0; e < 4; ++e) { v0[e] = sigm(v0[e] + bv[bj][0][e]); v1[e] = sigm(v1[e] + bv[bj][1][e]); } }
;                         __builtin_nontemporal_store(pack8(v0, v1), (u32x4*)(rowp + bj * HALF)); } }
	v_pk_add_f32 v[208:209], v[208:209], 1.0 op_sel_hi:[1,0]
	v_pk_add_f32 v[210:211], v[210:211], 1.0 op_sel_hi:[1,0]
	v_pk_add_f32 v[212:213], v[212:213], 1.0 op_sel_hi:[1,0]
	v_rcp_f32_e32 v206, v206
	v_rcp_f32_e32 v207, v207
	v_rcp_f32_e32 v208, v208
	v_rcp_f32_e32 v209, v209
	v_rcp_f32_e32 v210, v210
	v_rcp_f32_e32 v211, v211
	v_rcp_f32_e32 v212, v212
	v_rcp_f32_e32 v213, v213
	v_pk_add_f32 v[214:215], v[22:23], v[238:239]
	v_pk_add_f32 v[216:217], v[24:25], v[240:241]
	v_pk_add_f32 v[218:219], v[18:19], v[242:243]
	v_pk_add_f32 v[220:221], v[20:21], v[244:245]
	v_pk_mul_f32 v[214:215], v[214:215], s[24:25] op_sel_hi:[1,0]
	v_pk_mul_f32 v[216:217], v[216:217], s[24:25] op_sel_hi:[1,0]
	v_pk_mul_f32 v[218:219], v[218:219], s[24:25] op_sel_hi:[1,0]
	v_pk_mul_f32 v[220:221], v[220:221], s[24:25] op_sel_hi:[1,0]
	v_exp_f32_e32 v214, v214
	v_exp_f32_e32 v215, v215
	v_exp_f32_e32 v216, v216
	v_exp_f32_e32 v217, v217
	v_exp_f32_e32 v218, v218
	v_exp_f32_e32 v219, v219
	v_exp_f32_e32 v220, v220
	v_exp_f32_e32 v221, v221
	v_pk_add_f32 v[214:215], v[214:215], 1.0 op_sel_hi:[1,0]
	v_pk_add_f32 v[216:217], v[216:217], 1.0 op_sel_hi:[1,0]
	v_pk_add_f32 v[218:219], v[218:219], 1.0 op_sel_hi:[1,0]
	v_pk_add_f32 v[220:221], v[220:221], 1.0 op_sel_hi:[1,0]
	v_rcp_f32_e32 v214, v214
	v_rcp_f32_e32 v215, v215
	v_rcp_f32_e32 v216, v216
	v_rcp_f32_e32 v217, v217
	v_rcp_f32_e32 v218, v218
	v_rcp_f32_e32 v219, v219
	v_rcp_f32_e32 v220, v220
	v_rcp_f32_e32 v221, v221
	v_cvt_pk_bf16_f32 v156, v206, v207
	v_cvt_pk_bf16_f32 v157, v208, v209
	v_cvt_pk_bf16_f32 v158, v210, v211
	v_cvt_pk_bf16_f32 v159, v212, v213
	v_cvt_pk_bf16_f32 v160, v214, v215
	v_cvt_pk_bf16_f32 v161, v216, v217
	v_cvt_pk_bf16_f32 v162, v218, v219
	v_cvt_pk_bf16_f32 v163, v220, v221
	v_mov_b32_e32 v188, v160
	v_mov_b32_e32 v189, v161
	v_mov_b32_e32 v190, v162
	v_mov_b32_e32 v191, v163
	v_mov_b32_dpp v160, v156 row_ror:8 row_mask:0xf bank_mask:0x3
	v_mov_b32_dpp v161, v157 row_ror:8 row_mask:0xf bank_mask:0x3
	v_mov_b32_dpp v162, v158 row_ror:8 row_mask:0xf bank_mask:0x3
	v_mov_b32_dpp v163, v159 row_ror:8 row_mask:0xf bank_mask:0x3
	v_mov_b32_dpp v156, v188 row_ror:8 row_mask:0xf bank_mask:0xc
	v_mov_b32_dpp v157, v189 row_ror:8 row_mask:0xf bank_mask:0xc
	v_mov_b32_dpp v158, v190 row_ror:8 row_mask:0xf bank_mask:0xc
	v_mov_b32_dpp v159, v191 row_ror:8 row_mask:0xf bank_mask:0xc
	global_store_dwordx4 v138, v[156:159], s[6:7] sc1 nt
	global_store_dwordx4 v139, v[160:163], s[6:7] sc1 nt
	s_add_u32 s6, s6, 0x8000
	s_addc_u32 s7, s7, 0
	v_pk_add_f32 v[172:173], v[78:79], v[222:223]
	v_pk_add_f32 v[174:175], v[80:81], v[224:225]
	v_pk_add_f32 v[176:177], v[74:75], v[226:227]
	v_pk_add_f32 v[178:179], v[76:77], v[228:229]
	v_pk_mul_f32 v[172:173], v[172:173], s[24:25] op_sel_hi:[1,0]
	v_pk_mul_f32 v[174:175], v[174:175], s[24:25] op_sel_hi:[1,0]
	v_pk_mul_f32 v[176:177], v[176:177], s[24:25] op_sel_hi:[1,0]
	v_pk_mul_f32 v[178:179], v[178:179], s[24:25] op_sel_hi:[1,0]
	v_exp_f32_e32 v172, v172
	v_exp_f32_e32 v173, v173
	v_exp_f32_e32 v174, v174
	v_exp_f32_e32 v175, v175
	v_exp_f32_e32 v176, v176
	v_exp_f32_e32 v177, v177
	v_exp_f32_e32 v178, v178
	v_exp_f32_e32 v179, v179
	v_pk_add_f32 v[172:173], v[172:173], 1.0 op_sel_hi:[1,0]
	v_pk_add_f32 v[174:175], v[174:175], 1.0 op_sel_hi:[1,0]
	v_pk_add_f32 v[176:177], v[176:177], 1.0 op_sel_hi:[1,0]
	v_pk_add_f32 v[178:179], v[178:179], 1.0 op_sel_hi:[1,0]
	v_rcp_f32_e32 v172, v172
	v_rcp_f32_e32 v173, v173
	v_rcp_f32_e32 v174, v174
	v_rcp_f32_e32 v175, v175
	v_rcp_f32_e32 v176, v176
	v_rcp_f32_e32 v177, v177
	v_rcp_f32_e32 v178, v178
	v_rcp_f32_e32 v179, v179
	v_pk_add_f32 v[180:181], v[14:15], v[238:239]
	v_pk_add_f32 v[182:183], v[16:17], v[240:241]
	v_pk_add_f32 v[184:185], v[10:11], v[242:243]
	v_pk_add_f32 v[186:187], v[12:13], v[244:245]
	v_pk_mul_f32 v[180:181], v[180:181], s[24:25] op_sel_hi:[1,0]
	v_pk_mul_f32 v[182:183], v[182:183], s[24:25] op_sel_hi:[1,0]
	v_pk_mul_f32 v[184:185], v[184:185], s[24:25] op_sel_hi:[1,0]
	v_pk_mul_f32 v[186:187], v[186:187], s[24:25] op_sel_hi:[1,0]
	v_exp_f32_e32 v180, v180
	v_exp_f32_e32 v181, v181
	v_exp_f32_e32 v182, v182
	v_exp_f32_e32 v183, v183
	v_exp_f32_e32 v184, v184
	v_exp_f32_e32 v185, v185
	v_exp_f32_e32 v186, v186
	v_exp_f32_e32 v187, v187
	v_pk_add_f32 v[180:181], v[180:181], 1.0 op_sel_hi:[1,0]
	v_pk_add_f32 v[182:183], v[182:183], 1.0 op_sel_hi:[1,0]
	v_pk_add_f32 v[184:185], v[184:185], 1.0 op_sel_hi:[1,0]
	v_pk_add_f32 v[186:187], v[186:187], 1.0 op_sel_hi:[1,0]
; __device__ __forceinline__ unsigned cvt_pk_bf16(float lo, float hi) { unsigned r; asm volatile("v_cvt_pk_bf16_f32 %0, %1, %2" : "=v"(r) : "v"(lo), "v"(hi)); return r; }
; __device__ __forceinline__ float sigm(float x) { return __builtin_amdgcn_rcpf(1.f + __expf(-x)); }
; __device__ __forceinline__ u32x4 pack8(const f32x4 v0, const f32x4 v1) { u32x4 w; w.x = cvt_pk_bf16(v0[0], v0[1]); w.y = cvt_pk_bf16(v0[2], v0[3]); w.z = cvt_pk_bf16(v1[0], v1[1]); w.w = cvt_pk_bf16(v1[2], v1[3]); return w; }
;     __device__ __forceinline__ void operator()(f32x4 (&acc)[2][2][4][2], const Unit& u, int wr, int wc, int fr, int fq) const {
;     ...
;             for (int ai = 0; ai < 2; ++ai)
; #pragma unroll
;                 for (int m = 0; m < 4; ++m) { bf16_t* rowp = base + (size_t)(ai * HALF + m * 16) * LDZ;
; #pragma unroll
;                     for (int bj = 0; bj < 2; ++bj) { f32x4 v0 = acc[ai][bj][m][0], v1 = acc[ai][bj][m][1];
;                         if (kind == 1) {
; #pragma unroll
;                             for (int e = 0; e < 4; ++e) { v0[e] = v0[e] * sigm(v0[e]); v1[e] = v1[e] * sigm(v1[e]); } }
;                         else if (kind == 2) { v0 = v0 * (0.125f * LOG2E); v1 = v1 * (0.125f * LOG2E); }
;                         else if (kind == 3) {
; #pragma unroll
;                             for (int e = 0; e < 4; ++e) { v0[e] = sigm(v0[e] + bv[bj][0][e]); v1[e] = sigm(v1[e] + bv[bj][1][e]); } }
;                         __builtin_nontemporal_store(pack8(v0, v1), (u32x4*)(rowp + bj * HALF)); } }
	v_rcp_f32_e32 v180, v180
	v_rcp_f32_e32 v181, v181
	v_rcp_f32_e32 v182, v182
	v_rcp_f32_e32 v183, v183
	v_rcp_f32_e32 v184, v184
	v_rcp_f32_e32 v185, v185
	v_rcp_f32_e32 v186, v186
	v_rcp_f32_e32 v187, v187
	v_cvt_pk_bf16_f32 v130, v172, v173
	v_cvt_pk_bf16_f32 v131, v174, v175
	v_cvt_pk_bf16_f32 v132, v176, v177
	v_cvt_pk_bf16_f32 v133, v178, v179
	v_cvt_pk_bf16_f32 v134, v180, v181
	v_cvt_pk_bf16_f32 v135, v182, v183
	v_cvt_pk_bf16_f32 v136, v184, v185
	v_cvt_pk_bf16_f32 v137, v186, v187
	v_mov_b32_e32 v140, v134
	v_mov_b32_e32 v141, v135
	v_mov_b32_e32 v142, v136
	v_mov_b32_e32 v143, v137
	v_mov_b32_dpp v134, v130 row_ror:8 row_mask:0xf bank_mask:0x3
	v_mov_b32_dpp v135, v131 row_ror:8 row_mask:0xf bank_mask:0x3
	v_mov_b32_dpp v136, v132 row_ror:8 row_mask:0xf bank_mask:0x3
	v_mov_b32_dpp v137, v133 row_ror:8 row_mask:0xf bank_mask:0x3
	v_mov_b32_dpp v130, v140 row_ror:8 row_mask:0xf bank_mask:0xc
	v_mov_b32_dpp v131, v141 row_ror:8 row_mask:0xf bank_mask:0xc
	v_mov_b32_dpp v132, v142 row_ror:8 row_mask:0xf bank_mask:0xc
	v_mov_b32_dpp v133, v143 row_ror:8 row_mask:0xf bank_mask:0xc
	global_store_dwordx4 v138, v[130:133], s[6:7] sc1 nt
	global_store_dwordx4 v139, v[134:137], s[6:7] sc1 nt
	s_add_u32 s6, s6, 0x8000
	s_addc_u32 s7, s7, 0
	v_pk_add_f32 v[206:207], v[70:71], v[222:223]
	v_pk_add_f32 v[208:209], v[72:73], v[224:225]
	v_pk_add_f32 v[210:211], v[66:67], v[226:227]
	v_pk_add_f32 v[212:213], v[68:69], v[228:229]
	v_pk_mul_f32 v[206:207], v[206:207], s[24:25] op_sel_hi:[1,0]
	v_pk_mul_f32 v[208:209], v[208:209], s[24:25] op_sel_hi:[1,0]
	v_pk_mul_f32 v[210:211], v[210:211], s[24:25] op_sel_hi:[1,0]
	v_pk_mul_f32 v[212:213], v[212:213], s[24:25] op_sel_hi:[1,0]
	v_exp_f32_e32 v206, v206
	v_exp_f32_e32 v207, v207
	v_exp_f32_e32 v208, v208
	v_exp_f32_e32 v209, v209
	v_exp_f32_e32 v210, v210
	v_exp_f32_e32 v211, v211
	v_exp_f32_e32 v212, v212
	v_exp_f32_e32 v213, v213
	v_pk_add_f32 v[206:207], v[206:207], 1.0 op_sel_hi:[1,0]
	v_pk_add_f32 v[208:209], v[208:209], 1.0 op_sel_hi:[1,0]
	v_pk_add_f32 v[210:211], v[210:211], 1.0 op_sel_hi:[1,0]
	v_pk_add_f32 v[212:213], v[212:213], 1.0 op_sel_hi:[1,0]
	v_rcp_f32_e32 v206, v206
	v_rcp_f32_e32 v207, v207
	v_rcp_f32_e32 v208, v208
	v_rcp_f32_e32 v209, v209
	v_rcp_f32_e32 v210, v210
	v_rcp_f32_e32 v211, v211
	v_rcp_f32_e32 v212, v212
	v_rcp_f32_e32 v213, v213
	v_pk_add_f32 v[214:215], v[6:7], v[238:239]
	v_pk_add_f32 v[216:217], v[8:9], v[240:241]
	v_pk_add_f32 v[218:219], v[2:3], v[242:243]
	v_pk_add_f32 v[220:221], v[4:5], v[244:245]
	v_pk_mul_f32 v[214:215], v[214:215], s[24:25] op_sel_hi:[1,0]
	v_pk_mul_f32 v[216:217], v[216:217], s[24:25] op_sel_hi:[1,0]
	v_pk_mul_f32 v[218:219], v[218:219], s[24:25] op_sel_hi:[1,0]
	v_pk_mul_f32 v[220:221], v[220:221], s[24:25] op_sel_hi:[1,0]
	v_exp_f32_e32 v214, v214
	v_exp_f32_e32 v215, v215
	v_exp_f32_e32 v216, v216
	v_exp_f32_e32 v217, v217
	v_exp_f32_e32 v218, v218
	v_exp_f32_e32 v219, v219
	v_exp_f32_e32 v220, v220
	v_exp_f32_e32 v221, v221
	v_pk_add_f32 v[214:215], v[214:215], 1.0 op_sel_hi:[1,0]
	v_pk_add_f32 v[216:217], v[216:217], 1.0 op_sel_hi:[1,0]
	v_pk_add_f32 v[218:219], v[218:219], 1.0 op_sel_hi:[1,0]
	v_pk_add_f32 v[220:221], v[220:221], 1.0 op_sel_hi:[1,0]
	v_rcp_f32_e32 v214, v214
	v_rcp_f32_e32 v215, v215
	v_rcp_f32_e32 v216, v216
	v_rcp_f32_e32 v217, v217
	v_rcp_f32_e32 v218, v218
	v_rcp_f32_e32 v219, v219
	v_rcp_f32_e32 v220, v220
	v_rcp_f32_e32 v221, v221
	v_cvt_pk_bf16_f32 v156, v206, v207
	v_cvt_pk_bf16_f32 v157, v208, v209
	v_cvt_pk_bf16_f32 v158, v210, v211
	v_cvt_pk_bf16_f32 v159, v212, v213
	v_cvt_pk_bf16_f32 v160, v214, v215
	v_cvt_pk_bf16_f32 v161, v216, v217
	v_cvt_pk_bf16_f32 v162, v218, v219
	v_cvt_pk_bf16_f32 v163, v220, v221
	v_mov_b32_e32 v188, v160
	v_mov_b32_e32 v189, v161
	v_mov_b32_e32 v190, v162
	v_mov_b32_e32 v191, v163
	v_mov_b32_dpp v160, v156 row_ror:8 row_mask:0xf bank_mask:0x3
	v_mov_b32_dpp v161, v157 row_ror:8 row_mask:0xf bank_mask:0x3
	v_mov_b32_dpp v162, v158 row_ror:8 row_mask:0xf bank_mask:0x3
	v_mov_b32_dpp v163, v159 row_ror:8 row_mask:0xf bank_mask:0x3
	v_mov_b32_dpp v156, v188 row_ror:8 row_mask:0xf bank_mask:0xc
	v_mov_b32_dpp v157, v189 row_ror:8 row_mask:0xf bank_mask:0xc
	v_mov_b32_dpp v158, v190 row_ror:8 row_mask:0xf bank_mask:0xc
	v_mov_b32_dpp v159, v191 row_ror:8 row_mask:0xf bank_mask:0xc
	global_store_dwordx4 v138, v[156:159], s[6:7] sc1 nt
	global_store_dwordx4 v139, v[160:163], s[6:7] sc1 nt
	s_branch .Lepi1_done
